# chainzz2: chain2 plus zigzag k-order so every chain boundary shares an A or B operand register (hazard-checked); swaps the order of two f32 accumulations per accumulator per phase
# speedup vs baseline: 1.0136x; 1.0017x over previous
; #define PG8_STAGE(bufoff, gbase, voff) do { _Pragma("unroll") for (int _i = 0; _i < 2; ++_i) \
;         __builtin_amdgcn_global_load_lds((const unsigned*)((const char*)(gbase) + (voff)[_i]), (LAS unsigned*)(lds + (bufoff) + ldsw + _i * 8192), 16, 0, 0); } while (0)
; #define PG8_LDA(dst, b, h) do { _Pragma("unroll") for (int m = 0; m < 4; ++m) _Pragma("unroll") for (int k = 0; k < 2; ++k) dst[m][k] = *(const LAS bf16x8*)(lds + PG8_SA(b, h) + aoffk[k] + m * 2048); } while (0)
; #define PG8_LDB(dst, b, h) do { _Pragma("unroll") for (int n = 0; n < 2; ++n) _Pragma("unroll") for (int k = 0; k < 2; ++k) dst[n][k] = *(const LAS bf16x8*)(lds + PG8_SB(b, h) + boffk[k] + n * 2048); } while (0)
; #define PG8_WAIT_V(n) asm volatile("s_waitcnt vmcnt(" #n ")" ::: "memory")
; #define PG8_WAIT_L(n) asm volatile("s_waitcnt lgkmcnt(" #n ")" ::: "memory")
; #define PG8_BAR __builtin_amdgcn_s_barrier()
; #define PG8_SCHED __builtin_amdgcn_sched_barrier(0)
; template <class Epi, class Sched, class GemmT>
; __device__ __forceinline__ void gemm_phase(LAS unsigned char* lds, const GemmT& g, const Sched& S, const Epi& E, const int wid) {
;     ...
;             const int nt = cs.nt;
;             for (int t = 0; t < nt; t += 2) {
;                 const bool last = (t == nt - 2);
;                 const char* a1 = cA + (size_t)(t + 1) * kstep;
;                 const char* a2 = last ? ns.A : cA + (size_t)(t + 2) * kstep; const char* b2 = last ? ns.B : cB + (size_t)(t + 2) * kstep;
;                 const char* a3 = a2 + kstep; const char* b3 = b2 + kstep;
;                 unsigned vA2[2], vB2[2];
; #pragma unroll
;                 for (int i = 0; i < 2; ++i) { vA2[i] = last ? nvA[i] : voffA[i]; vB2[i] = last ? nvB[i] : voffB[i]; }
;                 const size_t hA2 = last ? nhA : hstepA, hB2 = last ? nhB : hstepB;
;                 PG8_LDB(B0, 0, 0); PG8_LDB(B1, 0, 1); PG8_SCHED; PG8_LDA(At, 0, 0); PG8_STAGE(PG8_SA(1, 1), a1 + hstepA, voffA);
;                 PG8_WAIT_V(8); PG8_WAIT_L(0); PG8_BAR; PG8_MMA(0, 0, At, B0); PG8_MMA(0, 1, At, B1); PG8_BAR; PG8_SCHED;
;                 PG8_LDA(At, 0, 1); PG8_STAGE(PG8_SB(0, 0), b2, vB2); PG8_STAGE(PG8_SB(0, 1), b2 + hB2, vB2); PG8_STAGE(PG8_SA(0, 0), a2, vA2);
;                 PG8_WAIT_V(8); PG8_WAIT_L(0); PG8_BAR; PG8_MMA(1, 0, At, B0); PG8_MMA(1, 1, At, B1); PG8_BAR; PG8_SCHED;
.LBB0_417:
	ds_read_b128 v[140:143], v192
	ds_read_b128 v[144:147], v193
	ds_read_b128 v[148:151], v194
	ds_read_b128 v[152:155], v195
	ds_read_b128 v[156:159], v196
	ds_read_b128 v[160:163], v197
	ds_read_b128 v[164:167], v198
	ds_read_b128 v[168:171], v199
	s_add_u32 s39, s84, 0xfff00080
	s_addc_u32 s40, s85, -1
	s_cmp_eq_u32 s38, 60
	s_cselect_b32 s87, s57, s40
	s_cselect_b32 s86, s56, s39
	s_cselect_b32 s71, s16, s37
	s_cselect_b32 s70, s5, s36
	v_lshl_add_u64 v[176:177], s[84:85], 0, v[128:129]
	s_add_i32 m0, s9, 0xc000
	ds_read_b128 v[172:175], v200
	ds_read_b128 v[208:211], v200 offset:2048
	ds_read_b128 v[212:215], v201
	ds_read_b128 v[216:219], v201 offset:2048
	ds_read_b128 v[220:223], v200 offset:4096
	ds_read_b128 v[224:227], v200 offset:6144
	ds_read_b128 v[230:233], v201 offset:4096
	ds_read_b128 v[234:237], v201 offset:6144
	global_load_lds_dwordx4 v[176:177], off
	v_lshl_add_u64 v[176:177], s[84:85], 0, v[132:133]
	s_add_i32 m0, s9, 0xe000
	s_nop 0
	global_load_lds_dwordx4 v[176:177], off
	s_waitcnt vmcnt(8)
	s_waitcnt lgkmcnt(0)
	s_barrier
	s_setprio 3
	s_waitcnt lgkmcnt(0)
	v_mfma_f32_16x16x32_bf16 v[124:127], v[140:143], v[172:175], v[124:127]
	v_mfma_f32_16x16x32_bf16 v[124:127], v[144:147], v[212:215], v[124:127]
	v_mfma_f32_16x16x32_bf16 v[120:123], v[152:155], v[212:215], v[120:123]
	v_mfma_f32_16x16x32_bf16 v[120:123], v[148:151], v[172:175], v[120:123]
	v_mfma_f32_16x16x32_bf16 v[112:115], v[148:151], v[208:211], v[112:115]
	v_mfma_f32_16x16x32_bf16 v[112:115], v[152:155], v[216:219], v[112:115]
	v_mfma_f32_16x16x32_bf16 v[116:119], v[144:147], v[216:219], v[116:119]
	v_mfma_f32_16x16x32_bf16 v[116:119], v[140:143], v[208:211], v[116:119]
	v_mfma_f32_16x16x32_bf16 v[100:103], v[140:143], v[220:223], v[100:103]
	v_mfma_f32_16x16x32_bf16 v[100:103], v[144:147], v[230:233], v[100:103]
	v_mfma_f32_16x16x32_bf16 v[96:99], v[152:155], v[230:233], v[96:99]
	v_mfma_f32_16x16x32_bf16 v[96:99], v[148:151], v[220:223], v[96:99]
	v_mfma_f32_16x16x32_bf16 v[76:79], v[148:151], v[224:227], v[76:79]
	v_mfma_f32_16x16x32_bf16 v[76:79], v[152:155], v[234:237], v[76:79]
	v_mfma_f32_16x16x32_bf16 v[84:87], v[144:147], v[234:237], v[84:87]
	v_mfma_f32_16x16x32_bf16 v[84:87], v[140:143], v[224:227], v[84:87]
	s_setprio 0
	s_setprio 3
	v_mfma_f32_16x16x32_bf16 v[108:111], v[156:159], v[172:175], v[108:111]
	v_mfma_f32_16x16x32_bf16 v[108:111], v[160:163], v[212:215], v[108:111]
	v_mfma_f32_16x16x32_bf16 v[104:107], v[168:171], v[212:215], v[104:107]
	v_mfma_f32_16x16x32_bf16 v[104:107], v[164:167], v[172:175], v[104:107]
	v_mfma_f32_16x16x32_bf16 v[88:91], v[164:167], v[208:211], v[88:91]
	v_mfma_f32_16x16x32_bf16 v[88:91], v[168:171], v[216:219], v[88:91]
	v_mfma_f32_16x16x32_bf16 v[92:95], v[160:163], v[216:219], v[92:95]
	v_mfma_f32_16x16x32_bf16 v[92:95], v[156:159], v[208:211], v[92:95]
	v_mfma_f32_16x16x32_bf16 v[68:71], v[156:159], v[220:223], v[68:71]
	v_mfma_f32_16x16x32_bf16 v[68:71], v[160:163], v[230:233], v[68:71]
	v_mfma_f32_16x16x32_bf16 v[64:67], v[168:171], v[230:233], v[64:67]
	v_mfma_f32_16x16x32_bf16 v[64:67], v[164:167], v[220:223], v[64:67]
	v_mfma_f32_16x16x32_bf16 v[40:43], v[164:167], v[224:227], v[40:43]
	v_mfma_f32_16x16x32_bf16 v[40:43], v[168:171], v[234:237], v[40:43]
	v_mfma_f32_16x16x32_bf16 v[48:51], v[160:163], v[234:237], v[48:51]
	v_mfma_f32_16x16x32_bf16 v[48:51], v[156:159], v[224:227], v[48:51]
	s_setprio 0
	s_barrier
	s_add_i32 s39, s35, s68
	v_lshl_add_u64 v[176:177], s[70:71], 0, v[130:131]
	s_mov_b32 m0, s39
	ds_read_b128 v[172:175], v200 offset:16384
	ds_read_b128 v[208:211], v200 offset:18432
	ds_read_b128 v[212:215], v201 offset:16384
	ds_read_b128 v[216:219], v201 offset:18432
	ds_read_b128 v[220:223], v200 offset:20480
	ds_read_b128 v[224:227], v200 offset:22528
	ds_read_b128 v[230:233], v201 offset:20480
	ds_read_b128 v[234:237], v201 offset:22528
	global_load_lds_dwordx4 v[176:177], off
	s_add_i32 m0, s39, 0x2000
	s_add_u32 s40, s70, 0x100000
	v_lshl_add_u64 v[180:181], s[70:71], 0, v[134:135]
	s_addc_u32 s41, s71, 0
	s_add_i32 s39, s69, s68
	global_load_lds_dwordx4 v[180:181], off
	v_lshl_add_u64 v[184:185], s[40:41], 0, v[130:131]
	s_mov_b32 m0, s39
	v_lshl_add_u64 v[188:189], s[86:87], 0, v[132:133]
	global_load_lds_dwordx4 v[184:185], off
	v_lshl_add_u64 v[184:185], s[40:41], 0, v[134:135]
	s_add_i32 m0, s39, 0x2000
	s_nop 0
	global_load_lds_dwordx4 v[184:185], off
	v_lshl_add_u64 v[184:185], s[86:87], 0, v[128:129]
	s_mov_b32 m0, s9
	s_nop 0
	global_load_lds_dwordx4 v[184:185], off
	s_mov_b32 m0, s29
	s_nop 0
	global_load_lds_dwordx4 v[188:189], off
	s_waitcnt vmcnt(8)
	s_waitcnt lgkmcnt(0)
	s_barrier
; #define PG8_STAGE(bufoff, gbase, voff) do { _Pragma("unroll") for (int _i = 0; _i < 2; ++_i) \
;         __builtin_amdgcn_global_load_lds((const unsigned*)((const char*)(gbase) + (voff)[_i]), (LAS unsigned*)(lds + (bufoff) + ldsw + _i * 8192), 16, 0, 0); } while (0)
; #define PG8_LDA(dst, b, h) do { _Pragma("unroll") for (int m = 0; m < 4; ++m) _Pragma("unroll") for (int k = 0; k < 2; ++k) dst[m][k] = *(const LAS bf16x8*)(lds + PG8_SA(b, h) + aoffk[k] + m * 2048); } while (0)
; #define PG8_LDB(dst, b, h) do { _Pragma("unroll") for (int n = 0; n < 2; ++n) _Pragma("unroll") for (int k = 0; k < 2; ++k) dst[n][k] = *(const LAS bf16x8*)(lds + PG8_SB(b, h) + boffk[k] + n * 2048); } while (0)
; #define PG8_WAIT_V(n) asm volatile("s_waitcnt vmcnt(" #n ")" ::: "memory")
; #define PG8_WAIT_L(n) asm volatile("s_waitcnt lgkmcnt(" #n ")" ::: "memory")
; #define PG8_BAR __builtin_amdgcn_s_barrier()
; #define PG8_SCHED __builtin_amdgcn_sched_barrier(0)
; template <class Epi, class Sched, class GemmT>
; __device__ __forceinline__ void gemm_phase(LAS unsigned char* lds, const GemmT& g, const Sched& S, const Epi& E, const int wid) {
;     ...
;                 PG8_WAIT_V(8); PG8_WAIT_L(0); PG8_BAR; PG8_MMA(1, 0, At, B0); PG8_MMA(1, 1, At, B1); PG8_BAR; PG8_SCHED;
;                 PG8_LDB(B0, 1, 0); PG8_LDB(B1, 1, 1); PG8_SCHED; PG8_LDA(At, 1, 0); PG8_STAGE(PG8_SA(0, 1), a2 + hA2, vA2);
;                 PG8_WAIT_V(8); PG8_WAIT_L(0); PG8_BAR; PG8_MMA(0, 0, At, B0); PG8_MMA(0, 1, At, B1); PG8_BAR; PG8_SCHED;
	s_setprio 3
	s_waitcnt lgkmcnt(0)
	v_mfma_f32_16x16x32_bf16 v[28:31], v[140:143], v[172:175], v[28:31]
	v_mfma_f32_16x16x32_bf16 v[28:31], v[144:147], v[212:215], v[28:31]
	v_mfma_f32_16x16x32_bf16 v[24:27], v[152:155], v[212:215], v[24:27]
	v_mfma_f32_16x16x32_bf16 v[24:27], v[148:151], v[172:175], v[24:27]
	v_mfma_f32_16x16x32_bf16 v[16:19], v[148:151], v[208:211], v[16:19]
	v_mfma_f32_16x16x32_bf16 v[16:19], v[152:155], v[216:219], v[16:19]
	v_mfma_f32_16x16x32_bf16 v[20:23], v[144:147], v[216:219], v[20:23]
	v_mfma_f32_16x16x32_bf16 v[20:23], v[140:143], v[208:211], v[20:23]
	v_mfma_f32_16x16x32_bf16 v[12:15], v[140:143], v[220:223], v[12:15]
	v_mfma_f32_16x16x32_bf16 v[12:15], v[144:147], v[230:233], v[12:15]
	v_mfma_f32_16x16x32_bf16 v[8:11], v[152:155], v[230:233], v[8:11]
	v_mfma_f32_16x16x32_bf16 v[8:11], v[148:151], v[220:223], v[8:11]
	v_mfma_f32_16x16x32_bf16 v[0:3], v[148:151], v[224:227], v[0:3]
	v_mfma_f32_16x16x32_bf16 v[0:3], v[152:155], v[234:237], v[0:3]
	v_mfma_f32_16x16x32_bf16 v[4:7], v[144:147], v[234:237], v[4:7]
	v_mfma_f32_16x16x32_bf16 v[4:7], v[140:143], v[224:227], v[4:7]
	s_setprio 0
	s_setprio 3
	v_mfma_f32_16x16x32_bf16 v[80:83], v[156:159], v[172:175], v[80:83]
	v_mfma_f32_16x16x32_bf16 v[80:83], v[160:163], v[212:215], v[80:83]
	v_mfma_f32_16x16x32_bf16 v[72:75], v[168:171], v[212:215], v[72:75]
	v_mfma_f32_16x16x32_bf16 v[72:75], v[164:167], v[172:175], v[72:75]
	v_mfma_f32_16x16x32_bf16 v[56:59], v[164:167], v[208:211], v[56:59]
	v_mfma_f32_16x16x32_bf16 v[56:59], v[168:171], v[216:219], v[56:59]
	v_mfma_f32_16x16x32_bf16 v[60:63], v[160:163], v[216:219], v[60:63]
	v_mfma_f32_16x16x32_bf16 v[60:63], v[156:159], v[208:211], v[60:63]
	v_mfma_f32_16x16x32_bf16 v[52:55], v[156:159], v[220:223], v[52:55]
	v_mfma_f32_16x16x32_bf16 v[52:55], v[160:163], v[230:233], v[52:55]
	v_mfma_f32_16x16x32_bf16 v[44:47], v[168:171], v[230:233], v[44:47]
	v_mfma_f32_16x16x32_bf16 v[44:47], v[164:167], v[220:223], v[44:47]
	v_mfma_f32_16x16x32_bf16 v[32:35], v[164:167], v[224:227], v[32:35]
	v_mfma_f32_16x16x32_bf16 v[32:35], v[168:171], v[234:237], v[32:35]
	v_mfma_f32_16x16x32_bf16 v[36:39], v[160:163], v[234:237], v[36:39]
	v_mfma_f32_16x16x32_bf16 v[36:39], v[156:159], v[224:227], v[36:39]
	s_setprio 0
	s_barrier
	s_add_i32 s39, 0, 0x18000
	s_add_i32 s48, 0, 0x1c000
	v_add_u32_e32 v140, s39, v187
	v_add_u32_e32 v144, s39, v190
	v_add_u32_e32 v156, s48, v187
	v_add_u32_e32 v160, s48, v190
	ds_read_b128 v[140:143], v140
	ds_read_b128 v[144:147], v144
	ds_read_b128 v[148:151], v202
	ds_read_b128 v[152:155], v203
	ds_read_b128 v[156:159], v156
	ds_read_b128 v[160:163], v160
	ds_read_b128 v[164:167], v204
	ds_read_b128 v[168:171], v205
	s_add_u32 s40, s86, 0x100000
	s_addc_u32 s41, s87, 0
	s_mov_b32 m0, s93
	v_lshl_add_u64 v[238:239], s[40:41], 0, v[128:129]
	ds_read_b128 v[172:175], v200 offset:32768
	ds_read_b128 v[208:211], v200 offset:34816
	ds_read_b128 v[212:215], v201 offset:32768
	ds_read_b128 v[216:219], v201 offset:34816
	ds_read_b128 v[220:223], v200 offset:36864
	ds_read_b128 v[224:227], v200 offset:38912
	ds_read_b128 v[230:233], v201 offset:36864
	ds_read_b128 v[234:237], v201 offset:38912
	global_load_lds_dwordx4 v[238:239], off
	v_lshl_add_u64 v[238:239], s[40:41], 0, v[132:133]
	s_mov_b32 m0, s6
	s_nop 0
	global_load_lds_dwordx4 v[238:239], off
	s_waitcnt vmcnt(8)
	s_waitcnt lgkmcnt(0)
	s_barrier
	s_setprio 3
	s_waitcnt lgkmcnt(0)
	v_mfma_f32_16x16x32_bf16 v[124:127], v[140:143], v[172:175], v[124:127]
	v_mfma_f32_16x16x32_bf16 v[124:127], v[144:147], v[212:215], v[124:127]
	v_mfma_f32_16x16x32_bf16 v[120:123], v[152:155], v[212:215], v[120:123]
	v_mfma_f32_16x16x32_bf16 v[120:123], v[148:151], v[172:175], v[120:123]
	v_mfma_f32_16x16x32_bf16 v[112:115], v[148:151], v[208:211], v[112:115]
	v_mfma_f32_16x16x32_bf16 v[112:115], v[152:155], v[216:219], v[112:115]
	v_mfma_f32_16x16x32_bf16 v[116:119], v[144:147], v[216:219], v[116:119]
	v_mfma_f32_16x16x32_bf16 v[116:119], v[140:143], v[208:211], v[116:119]
	v_mfma_f32_16x16x32_bf16 v[100:103], v[140:143], v[220:223], v[100:103]
	v_mfma_f32_16x16x32_bf16 v[100:103], v[144:147], v[230:233], v[100:103]
	v_mfma_f32_16x16x32_bf16 v[96:99], v[152:155], v[230:233], v[96:99]
	v_mfma_f32_16x16x32_bf16 v[96:99], v[148:151], v[220:223], v[96:99]
	v_mfma_f32_16x16x32_bf16 v[76:79], v[148:151], v[224:227], v[76:79]
	v_mfma_f32_16x16x32_bf16 v[76:79], v[152:155], v[234:237], v[76:79]
	v_mfma_f32_16x16x32_bf16 v[84:87], v[144:147], v[234:237], v[84:87]
	v_mfma_f32_16x16x32_bf16 v[84:87], v[140:143], v[224:227], v[84:87]
	s_setprio 0
	s_setprio 3
	v_mfma_f32_16x16x32_bf16 v[108:111], v[156:159], v[172:175], v[108:111]
	v_mfma_f32_16x16x32_bf16 v[108:111], v[160:163], v[212:215], v[108:111]
	v_mfma_f32_16x16x32_bf16 v[104:107], v[168:171], v[212:215], v[104:107]
	v_mfma_f32_16x16x32_bf16 v[104:107], v[164:167], v[172:175], v[104:107]
	v_mfma_f32_16x16x32_bf16 v[88:91], v[164:167], v[208:211], v[88:91]
	v_mfma_f32_16x16x32_bf16 v[88:91], v[168:171], v[216:219], v[88:91]
	v_mfma_f32_16x16x32_bf16 v[92:95], v[160:163], v[216:219], v[92:95]
	v_mfma_f32_16x16x32_bf16 v[92:95], v[156:159], v[208:211], v[92:95]
	v_mfma_f32_16x16x32_bf16 v[68:71], v[156:159], v[220:223], v[68:71]
	v_mfma_f32_16x16x32_bf16 v[68:71], v[160:163], v[230:233], v[68:71]
	v_mfma_f32_16x16x32_bf16 v[64:67], v[168:171], v[230:233], v[64:67]
	v_mfma_f32_16x16x32_bf16 v[64:67], v[164:167], v[220:223], v[64:67]
	v_mfma_f32_16x16x32_bf16 v[40:43], v[164:167], v[224:227], v[40:43]
	v_mfma_f32_16x16x32_bf16 v[40:43], v[168:171], v[234:237], v[40:43]
	v_mfma_f32_16x16x32_bf16 v[48:51], v[160:163], v[234:237], v[48:51]
	v_mfma_f32_16x16x32_bf16 v[48:51], v[156:159], v[224:227], v[48:51]
	s_setprio 0
	s_barrier
; #define PG8_STAGE(bufoff, gbase, voff) do { _Pragma("unroll") for (int _i = 0; _i < 2; ++_i) \
;         __builtin_amdgcn_global_load_lds((const unsigned*)((const char*)(gbase) + (voff)[_i]), (LAS unsigned*)(lds + (bufoff) + ldsw + _i * 8192), 16, 0, 0); } while (0)
; #define PG8_LDA(dst, b, h) do { _Pragma("unroll") for (int m = 0; m < 4; ++m) _Pragma("unroll") for (int k = 0; k < 2; ++k) dst[m][k] = *(const LAS bf16x8*)(lds + PG8_SA(b, h) + aoffk[k] + m * 2048); } while (0)
; #define PG8_WAIT_V(n) asm volatile("s_waitcnt vmcnt(" #n ")" ::: "memory")
; #define PG8_WAIT_L(n) asm volatile("s_waitcnt lgkmcnt(" #n ")" ::: "memory")
; #define PG8_BAR __builtin_amdgcn_s_barrier()
; #define PG8_SCHED __builtin_amdgcn_sched_barrier(0)
; template <class Epi, class Sched, class GemmT>
; __device__ __forceinline__ void gemm_phase(LAS unsigned char* lds, const GemmT& g, const Sched& S, const Epi& E, const int wid) {
;     ...
;                 PG8_LDA(At, 1, 1); PG8_STAGE(PG8_SB(1, 0), b3, vB2); PG8_STAGE(PG8_SB(1, 1), b3 + hB2, vB2); PG8_STAGE(PG8_SA(1, 0), a3, vA2);
;                 PG8_WAIT_V(8); PG8_WAIT_L(0); PG8_BAR; PG8_MMA(1, 0, At, B0); PG8_MMA(1, 1, At, B1); PG8_BAR; PG8_SCHED;
;             }
	s_add_i32 s39, s39, s68
	v_lshl_add_u64 v[176:177], v[176:177], 0, s[66:67]
	s_mov_b32 m0, s39
	ds_read_b128 v[172:175], v200 offset:49152
	ds_read_b128 v[208:211], v200 offset:51200
	ds_read_b128 v[212:215], v201 offset:49152
	ds_read_b128 v[216:219], v201 offset:51200
	ds_read_b128 v[220:223], v200 offset:53248
	ds_read_b128 v[224:227], v200 offset:55296
	ds_read_b128 v[230:233], v201 offset:53248
	ds_read_b128 v[234:237], v201 offset:55296
	global_load_lds_dwordx4 v[176:177], off
	s_add_i32 m0, s39, 0x2000
	s_add_u32 s40, s70, 0x100080
	v_lshl_add_u64 v[176:177], v[180:181], 0, s[66:67]
	s_addc_u32 s41, s71, 0
	s_add_i32 s39, s48, s68
	global_load_lds_dwordx4 v[176:177], off
	v_lshl_add_u64 v[176:177], s[40:41], 0, v[130:131]
	s_mov_b32 m0, s39
	s_nop 0
	global_load_lds_dwordx4 v[176:177], off
	v_lshl_add_u64 v[176:177], s[40:41], 0, v[134:135]
	s_add_i32 m0, s39, 0x2000
	s_nop 0
	global_load_lds_dwordx4 v[176:177], off
	v_lshl_add_u64 v[176:177], v[184:185], 0, s[66:67]
	s_mov_b32 m0, s7
	s_nop 0
	global_load_lds_dwordx4 v[176:177], off
	v_lshl_add_u64 v[176:177], v[188:189], 0, s[66:67]
	s_mov_b32 m0, s12
	s_nop 0
	global_load_lds_dwordx4 v[176:177], off
	s_waitcnt vmcnt(8)
	s_waitcnt lgkmcnt(0)
	s_barrier
	s_setprio 3
	s_waitcnt lgkmcnt(0)
	v_mfma_f32_16x16x32_bf16 v[28:31], v[140:143], v[172:175], v[28:31]
	v_mfma_f32_16x16x32_bf16 v[28:31], v[144:147], v[212:215], v[28:31]
	v_mfma_f32_16x16x32_bf16 v[24:27], v[152:155], v[212:215], v[24:27]
	v_mfma_f32_16x16x32_bf16 v[24:27], v[148:151], v[172:175], v[24:27]
	v_mfma_f32_16x16x32_bf16 v[16:19], v[148:151], v[208:211], v[16:19]
	v_mfma_f32_16x16x32_bf16 v[16:19], v[152:155], v[216:219], v[16:19]
	v_mfma_f32_16x16x32_bf16 v[20:23], v[144:147], v[216:219], v[20:23]
	v_mfma_f32_16x16x32_bf16 v[20:23], v[140:143], v[208:211], v[20:23]
	v_mfma_f32_16x16x32_bf16 v[12:15], v[140:143], v[220:223], v[12:15]
	v_mfma_f32_16x16x32_bf16 v[12:15], v[144:147], v[230:233], v[12:15]
	v_mfma_f32_16x16x32_bf16 v[8:11], v[152:155], v[230:233], v[8:11]
	v_mfma_f32_16x16x32_bf16 v[8:11], v[148:151], v[220:223], v[8:11]
	v_mfma_f32_16x16x32_bf16 v[0:3], v[148:151], v[224:227], v[0:3]
	v_mfma_f32_16x16x32_bf16 v[0:3], v[152:155], v[234:237], v[0:3]
	v_mfma_f32_16x16x32_bf16 v[4:7], v[144:147], v[234:237], v[4:7]
	v_mfma_f32_16x16x32_bf16 v[4:7], v[140:143], v[224:227], v[4:7]
	s_setprio 0
	s_setprio 3
	v_mfma_f32_16x16x32_bf16 v[80:83], v[156:159], v[172:175], v[80:83]
	v_mfma_f32_16x16x32_bf16 v[80:83], v[160:163], v[212:215], v[80:83]
	v_mfma_f32_16x16x32_bf16 v[72:75], v[168:171], v[212:215], v[72:75]
	v_mfma_f32_16x16x32_bf16 v[72:75], v[164:167], v[172:175], v[72:75]
	v_mfma_f32_16x16x32_bf16 v[56:59], v[164:167], v[208:211], v[56:59]
	v_mfma_f32_16x16x32_bf16 v[56:59], v[168:171], v[216:219], v[56:59]
	v_mfma_f32_16x16x32_bf16 v[60:63], v[160:163], v[216:219], v[60:63]
	v_mfma_f32_16x16x32_bf16 v[60:63], v[156:159], v[208:211], v[60:63]
	v_mfma_f32_16x16x32_bf16 v[52:55], v[156:159], v[220:223], v[52:55]
	v_mfma_f32_16x16x32_bf16 v[52:55], v[160:163], v[230:233], v[52:55]
	v_mfma_f32_16x16x32_bf16 v[44:47], v[168:171], v[230:233], v[44:47]
	v_mfma_f32_16x16x32_bf16 v[44:47], v[164:167], v[220:223], v[44:47]
	v_mfma_f32_16x16x32_bf16 v[32:35], v[164:167], v[224:227], v[32:35]
	v_mfma_f32_16x16x32_bf16 v[32:35], v[168:171], v[234:237], v[32:35]
	v_mfma_f32_16x16x32_bf16 v[36:39], v[160:163], v[234:237], v[36:39]
	v_mfma_f32_16x16x32_bf16 v[36:39], v[156:159], v[224:227], v[36:39]
	s_setprio 0
	s_barrier
	s_add_i32 s38, s38, 2
	s_add_u32 s84, s84, 0x100
	s_addc_u32 s85, s85, 0
	s_add_u32 s36, s36, 0x100
	s_addc_u32 s37, s37, 0
	s_cmp_gt_u32 s38, 61
	s_cbranch_scc0 .LBB0_417
	s_and_b64 vcc, exec, s[20:21]
	s_cbranch_vccz .LBB0_420
	s_barrier

; #define PG8_STAGE(bufoff, gbase, voff) do { _Pragma("unroll") for (int _i = 0; _i < 2; ++_i) \
;         __builtin_amdgcn_global_load_lds((const unsigned*)((const char*)(gbase) + (voff)[_i]), (LAS unsigned*)(lds + (bufoff) + ldsw + _i * 8192), 16, 0, 0); } while (0)
; #define PG8_LDA(dst, b, h) do { _Pragma("unroll") for (int m = 0; m < 4; ++m) _Pragma("unroll") for (int k = 0; k < 2; ++k) dst[m][k] = *(const LAS bf16x8*)(lds + PG8_SA(b, h) + aoffk[k] + m * 2048); } while (0)
; #define PG8_WAIT_V(n) asm volatile("s_waitcnt vmcnt(" #n ")" ::: "memory")
; #define PG8_WAIT_L(n) asm volatile("s_waitcnt lgkmcnt(" #n ")" ::: "memory")
; template <class Epi, class Sched, class GemmT>
; __device__ __forceinline__ void gemm_phase(LAS unsigned char* lds, const GemmT& g, const Sched& S, const Epi& E, const int wid) {
;     ...
;             const Seg ns = (sgi + 1 < NSEG) ? g.seg(cur, sgi + 1) : g.seg(has_next ? nxt : cur, 0);
;             unsigned nvA[2], nvB[2]; size_t nhA, nhB;
;             if constexpr (GemmT::UNIFORM) { nvA[0] = voffA[0]; nvA[1] = voffA[1]; nvB[0] = voffB[0]; nvB[1] = voffB[1]; nhA = hstepA; nhB = hstepB; }
;             else PG8_VOFFS(nvA, nvB, nhA, nhB, ns);
;             const int nt = cs.nt;
;             for (int t = 0; t < nt; t += 2) {
;                 const bool last = (t == nt - 2);
;                 const char* a1 = cA + (size_t)(t + 1) * kstep;
;                 const char* a2 = last ? ns.A : cA + (size_t)(t + 2) * kstep; const char* b2 = last ? ns.B : cB + (size_t)(t + 2) * kstep;
;                 const char* a3 = a2 + kstep; const char* b3 = b2 + kstep;
;                 unsigned vA2[2], vB2[2];
; #pragma unroll
;                 for (int i = 0; i < 2; ++i) { vA2[i] = last ? nvA[i] : voffA[i]; vB2[i] = last ? nvB[i] : voffB[i]; }
;                 const size_t hA2 = last ? nhA : hstepA, hB2 = last ? nhB : hstepB;
;                 PG8_LDB(B0, 0, 0); PG8_LDB(B1, 0, 1); PG8_SCHED; PG8_LDA(At, 0, 0); PG8_STAGE(PG8_SA(1, 1), a1 + hstepA, voffA);
;                 PG8_WAIT_V(8); PG8_WAIT_L(0); PG8_BAR; PG8_MMA(0, 0, At, B0); PG8_MMA(0, 1, At, B1); PG8_BAR; PG8_SCHED;
;                 PG8_LDA(At, 0, 1); PG8_STAGE(PG8_SB(0, 0), b2, vB2); PG8_STAGE(PG8_SB(0, 1), b2 + hB2, vB2); PG8_STAGE(PG8_SA(0, 0), a2, vA2);
;                 PG8_WAIT_V(8); PG8_WAIT_L(0); PG8_BAR; PG8_MMA(1, 0, At, B0); PG8_MMA(1, 1, At, B1); PG8_BAR; PG8_SCHED;
.LBB0_764:
	s_cmp_eq_u32 s43, s56
	s_cselect_b64 vcc, -1, 0
	s_add_i32 s90, s90, 2
	v_add_u32_e32 v131, s62, v208
	s_add_u32 s48, s50, s56
	v_add_u32_e32 v133, s62, v209
	ds_read_b128 v[144:147], v131
	ds_read_b128 v[148:151], v133
	v_add_u32_e32 v131, s63, v208
	s_addc_u32 s49, s51, s57
	v_add_u32_e32 v133, s63, v209
	ds_read_b128 v[152:155], v131
	ds_read_b128 v[156:159], v133
	v_add_u32_e32 v131, s64, v208
	s_add_u32 s58, s48, 0x100
	v_add_u32_e32 v133, s64, v209
	ds_read_b128 v[160:163], v131
	ds_read_b128 v[164:167], v133
	v_add_u32_e32 v131, s65, v208
	s_addc_u32 s59, s49, 0
	v_add_u32_e32 v133, s65, v209
	ds_read_b128 v[168:171], v131
	ds_read_b128 v[172:175], v133
	s_and_b64 s[48:49], vcc, exec
	s_cselect_b32 s59, s19, s59
	s_cselect_b32 s58, s18, s58
	s_add_u32 s60, s85, s56
	s_addc_u32 s61, s89, s57
	s_and_b64 s[48:49], vcc, exec
	v_cndmask_b32_e32 v138, v132, v190, vcc
	v_cndmask_b32_e32 v0, v143, v214, vcc
	v_cndmask_b32_e32 v140, v130, v194, vcc
	v_cndmask_b32_e32 v188, v142, v192, vcc
	s_cselect_b32 s61, s13, s61
	s_cselect_b32 s60, s12, s60
	s_cselect_b32 s91, 0, s45
	s_cselect_b32 s92, s6, s44
	v_lshl_add_u64 v[202:203], v[134:135], 0, s[56:57]
	s_add_i32 m0, s14, 0xc000
	ds_read_b128 v[176:179], v212
	ds_read_b128 v[180:183], v212 offset:2048
	ds_read_b128 v[184:187], v213
	ds_read_b128 v[216:219], v213 offset:2048
	ds_read_b128 v[220:223], v212 offset:4096
	ds_read_b128 v[224:227], v212 offset:6144
	ds_read_b128 v[230:233], v213 offset:4096
	ds_read_b128 v[234:237], v213 offset:6144
	global_load_lds_dwordx4 v[202:203], off
	v_lshl_add_u64 v[202:203], v[136:137], 0, s[56:57]
	s_add_i32 m0, s14, 0xe000
	s_nop 0
	global_load_lds_dwordx4 v[202:203], off
	s_waitcnt vmcnt(8)
	s_waitcnt lgkmcnt(0)
	s_barrier
	s_setprio 3
	s_waitcnt lgkmcnt(0)
	v_mfma_f32_16x16x32_bf16 v[126:129], v[144:147], v[176:179], v[126:129]
	v_mfma_f32_16x16x32_bf16 v[126:129], v[148:151], v[184:187], v[126:129]
	v_mfma_f32_16x16x32_bf16 v[122:125], v[156:159], v[184:187], v[122:125]
	v_mfma_f32_16x16x32_bf16 v[122:125], v[152:155], v[176:179], v[122:125]
	v_mfma_f32_16x16x32_bf16 v[106:109], v[152:155], v[180:183], v[106:109]
	v_mfma_f32_16x16x32_bf16 v[106:109], v[156:159], v[216:219], v[106:109]
	v_mfma_f32_16x16x32_bf16 v[110:113], v[148:151], v[216:219], v[110:113]
	v_mfma_f32_16x16x32_bf16 v[110:113], v[144:147], v[180:183], v[110:113]
	v_mfma_f32_16x16x32_bf16 v[94:97], v[144:147], v[220:223], v[94:97]
	v_mfma_f32_16x16x32_bf16 v[94:97], v[148:151], v[230:233], v[94:97]
	v_mfma_f32_16x16x32_bf16 v[90:93], v[156:159], v[230:233], v[90:93]
	v_mfma_f32_16x16x32_bf16 v[90:93], v[152:155], v[220:223], v[90:93]
	v_mfma_f32_16x16x32_bf16 v[74:77], v[152:155], v[224:227], v[74:77]
	v_mfma_f32_16x16x32_bf16 v[74:77], v[156:159], v[234:237], v[74:77]
	v_mfma_f32_16x16x32_bf16 v[78:81], v[148:151], v[234:237], v[78:81]
	v_mfma_f32_16x16x32_bf16 v[78:81], v[144:147], v[224:227], v[78:81]
	s_setprio 0
	s_setprio 3
	v_mfma_f32_16x16x32_bf16 v[118:121], v[160:163], v[176:179], v[118:121]
	v_mfma_f32_16x16x32_bf16 v[118:121], v[164:167], v[184:187], v[118:121]
	v_mfma_f32_16x16x32_bf16 v[114:117], v[172:175], v[184:187], v[114:117]
	v_mfma_f32_16x16x32_bf16 v[114:117], v[168:171], v[176:179], v[114:117]
	v_mfma_f32_16x16x32_bf16 v[98:101], v[168:171], v[180:183], v[98:101]
	v_mfma_f32_16x16x32_bf16 v[98:101], v[172:175], v[216:219], v[98:101]
	v_mfma_f32_16x16x32_bf16 v[102:105], v[164:167], v[216:219], v[102:105]
	v_mfma_f32_16x16x32_bf16 v[102:105], v[160:163], v[180:183], v[102:105]
	v_mfma_f32_16x16x32_bf16 v[86:89], v[160:163], v[220:223], v[86:89]
	v_mfma_f32_16x16x32_bf16 v[86:89], v[164:167], v[230:233], v[86:89]
	v_mfma_f32_16x16x32_bf16 v[82:85], v[172:175], v[230:233], v[82:85]
	v_mfma_f32_16x16x32_bf16 v[82:85], v[168:171], v[220:223], v[82:85]
	v_mfma_f32_16x16x32_bf16 v[66:69], v[168:171], v[224:227], v[66:69]
	v_mfma_f32_16x16x32_bf16 v[66:69], v[172:175], v[234:237], v[66:69]
	v_mfma_f32_16x16x32_bf16 v[70:73], v[164:167], v[234:237], v[70:73]
	v_mfma_f32_16x16x32_bf16 v[70:73], v[160:163], v[224:227], v[70:73]
	s_setprio 0
	s_barrier
	s_add_i32 s48, s62, s68
	s_mov_b32 m0, s48
	ds_read_b128 v[176:179], v212 offset:16384
	ds_read_b128 v[180:183], v213 offset:16384
	ds_read_b128 v[184:187], v212 offset:18432
	ds_read_b128 v[216:219], v213 offset:18432
	ds_read_b128 v[220:223], v212 offset:20480
	ds_read_b128 v[224:227], v213 offset:20480
	ds_read_b128 v[230:233], v212 offset:22528
	ds_read_b128 v[234:237], v213 offset:22528
	global_load_lds_dwordx4 v0, s[60:61]
	s_add_i32 m0, s48, 0x2000
	v_mov_b32_e32 v189, v1
	s_add_u32 s48, s60, s92
	v_lshl_add_u64 v[202:203], s[60:61], 0, v[0:1]
	v_lshl_add_u64 v[238:239], s[60:61], 0, v[188:189]
	global_load_lds_dwordx4 v188, s[60:61]
	s_addc_u32 s49, s61, s91
	s_add_i32 s60, s64, s68
	s_mov_b32 m0, s60
	v_mov_b32_e32 v139, v1
	global_load_lds_dwordx4 v0, s[48:49]
	s_add_i32 m0, s60, 0x2000
	v_mov_b32_e32 v141, v1
	global_load_lds_dwordx4 v188, s[48:49]
	s_mov_b32 m0, s14
	v_lshl_add_u64 v[240:241], s[48:49], 0, v[0:1]
	global_load_lds_dwordx4 v138, s[58:59]
	s_mov_b32 m0, s15
	v_lshl_add_u64 v[242:243], s[48:49], 0, v[188:189]
	global_load_lds_dwordx4 v140, s[58:59]
	s_waitcnt vmcnt(8)
	s_waitcnt lgkmcnt(0)
	v_lshl_add_u64 v[188:189], s[58:59], 0, v[138:139]
	v_lshl_add_u64 v[244:245], s[58:59], 0, v[140:141]
	s_barrier
; #define PG8_STAGE(bufoff, gbase, voff) do { _Pragma("unroll") for (int _i = 0; _i < 2; ++_i) \
;         __builtin_amdgcn_global_load_lds((const unsigned*)((const char*)(gbase) + (voff)[_i]), (LAS unsigned*)(lds + (bufoff) + ldsw + _i * 8192), 16, 0, 0); } while (0)
; #define PG8_LDA(dst, b, h) do { _Pragma("unroll") for (int m = 0; m < 4; ++m) _Pragma("unroll") for (int k = 0; k < 2; ++k) dst[m][k] = *(const LAS bf16x8*)(lds + PG8_SA(b, h) + aoffk[k] + m * 2048); } while (0)
; #define PG8_LDB(dst, b, h) do { _Pragma("unroll") for (int n = 0; n < 2; ++n) _Pragma("unroll") for (int k = 0; k < 2; ++k) dst[n][k] = *(const LAS bf16x8*)(lds + PG8_SB(b, h) + boffk[k] + n * 2048); } while (0)
; #define PG8_WAIT_V(n) asm volatile("s_waitcnt vmcnt(" #n ")" ::: "memory")
; #define PG8_WAIT_L(n) asm volatile("s_waitcnt lgkmcnt(" #n ")" ::: "memory")
; #define PG8_BAR __builtin_amdgcn_s_barrier()
; #define PG8_SCHED __builtin_amdgcn_sched_barrier(0)
; template <class Epi, class Sched, class GemmT>
; __device__ __forceinline__ void gemm_phase(LAS unsigned char* lds, const GemmT& g, const Sched& S, const Epi& E, const int wid) {
;     ...
;                 PG8_WAIT_V(8); PG8_WAIT_L(0); PG8_BAR; PG8_MMA(1, 0, At, B0); PG8_MMA(1, 1, At, B1); PG8_BAR; PG8_SCHED;
;                 PG8_LDB(B0, 1, 0); PG8_LDB(B1, 1, 1); PG8_SCHED; PG8_LDA(At, 1, 0); PG8_STAGE(PG8_SA(0, 1), a2 + hA2, vA2);
;                 PG8_WAIT_V(8); PG8_WAIT_L(0); PG8_BAR; PG8_MMA(0, 0, At, B0); PG8_MMA(0, 1, At, B1); PG8_BAR; PG8_SCHED;
	s_setprio 3
	s_waitcnt lgkmcnt(0)
	v_mfma_f32_16x16x32_bf16 v[62:65], v[144:147], v[176:179], v[62:65]
	v_mfma_f32_16x16x32_bf16 v[62:65], v[148:151], v[180:183], v[62:65]
	v_mfma_f32_16x16x32_bf16 v[58:61], v[156:159], v[180:183], v[58:61]
	v_mfma_f32_16x16x32_bf16 v[58:61], v[152:155], v[176:179], v[58:61]
	v_mfma_f32_16x16x32_bf16 v[42:45], v[152:155], v[184:187], v[42:45]
	v_mfma_f32_16x16x32_bf16 v[42:45], v[156:159], v[216:219], v[42:45]
	v_mfma_f32_16x16x32_bf16 v[46:49], v[148:151], v[216:219], v[46:49]
	v_mfma_f32_16x16x32_bf16 v[46:49], v[144:147], v[184:187], v[46:49]
	v_mfma_f32_16x16x32_bf16 v[30:33], v[144:147], v[220:223], v[30:33]
	v_mfma_f32_16x16x32_bf16 v[30:33], v[148:151], v[224:227], v[30:33]
	v_mfma_f32_16x16x32_bf16 v[22:25], v[156:159], v[224:227], v[22:25]
	v_mfma_f32_16x16x32_bf16 v[22:25], v[152:155], v[220:223], v[22:25]
	v_mfma_f32_16x16x32_bf16 v[6:9], v[152:155], v[230:233], v[6:9]
	v_mfma_f32_16x16x32_bf16 v[6:9], v[156:159], v[234:237], v[6:9]
	v_mfma_f32_16x16x32_bf16 v[14:17], v[148:151], v[234:237], v[14:17]
	v_mfma_f32_16x16x32_bf16 v[14:17], v[144:147], v[230:233], v[14:17]
	s_setprio 0
	s_setprio 3
	v_mfma_f32_16x16x32_bf16 v[54:57], v[160:163], v[176:179], v[54:57]
	v_mfma_f32_16x16x32_bf16 v[54:57], v[164:167], v[180:183], v[54:57]
	v_mfma_f32_16x16x32_bf16 v[50:53], v[172:175], v[180:183], v[50:53]
	v_mfma_f32_16x16x32_bf16 v[50:53], v[168:171], v[176:179], v[50:53]
	v_mfma_f32_16x16x32_bf16 v[34:37], v[168:171], v[184:187], v[34:37]
	v_mfma_f32_16x16x32_bf16 v[34:37], v[172:175], v[216:219], v[34:37]
	v_mfma_f32_16x16x32_bf16 v[38:41], v[164:167], v[216:219], v[38:41]
	v_mfma_f32_16x16x32_bf16 v[38:41], v[160:163], v[184:187], v[38:41]
	v_mfma_f32_16x16x32_bf16 v[26:29], v[160:163], v[220:223], v[26:29]
	v_mfma_f32_16x16x32_bf16 v[26:29], v[164:167], v[224:227], v[26:29]
	v_mfma_f32_16x16x32_bf16 v[18:21], v[172:175], v[224:227], v[18:21]
	v_mfma_f32_16x16x32_bf16 v[18:21], v[168:171], v[220:223], v[18:21]
	v_mfma_f32_16x16x32_bf16 v[2:5], v[168:171], v[230:233], v[2:5]
	v_mfma_f32_16x16x32_bf16 v[2:5], v[172:175], v[234:237], v[2:5]
	v_mfma_f32_16x16x32_bf16 v[10:13], v[164:167], v[234:237], v[10:13]
	v_mfma_f32_16x16x32_bf16 v[10:13], v[160:163], v[230:233], v[10:13]
	s_setprio 0
	s_barrier
	s_add_i32 s60, 0, 0x18000
	v_add_u32_e32 v0, s60, v208
	v_add_u32_e32 v131, s60, v209
	ds_read_b128 v[144:147], v0
	ds_read_b128 v[148:151], v131
	v_add_u32_e32 v0, s66, v208
	s_add_i32 s61, 0, 0x1c000
	v_add_u32_e32 v131, s66, v209
	ds_read_b128 v[152:155], v0
	ds_read_b128 v[156:159], v131
	v_add_u32_e32 v0, s61, v208
	v_add_u32_e32 v131, s61, v209
	ds_read_b128 v[160:163], v0
	ds_read_b128 v[164:167], v131
	v_add_u32_e32 v0, s67, v208
	v_add_u32_e32 v131, s67, v209
	ds_read_b128 v[168:171], v0
	ds_read_b128 v[172:175], v131
	s_add_u32 s48, s58, s92
	s_addc_u32 s49, s59, s91
	s_mov_b32 m0, s34
	ds_read_b128 v[176:179], v212 offset:32768
	ds_read_b128 v[180:183], v212 offset:34816
	ds_read_b128 v[184:187], v213 offset:32768
	ds_read_b128 v[216:219], v213 offset:34816
	ds_read_b128 v[220:223], v212 offset:36864
	ds_read_b128 v[224:227], v212 offset:38912
	ds_read_b128 v[230:233], v213 offset:36864
	ds_read_b128 v[234:237], v213 offset:38912
	global_load_lds_dwordx4 v138, s[48:49]
	s_mov_b32 m0, s35
	s_nop 0
	global_load_lds_dwordx4 v140, s[48:49]
	s_waitcnt vmcnt(8)
	s_waitcnt lgkmcnt(0)
	s_barrier
	s_setprio 3
	s_waitcnt lgkmcnt(0)
	v_mfma_f32_16x16x32_bf16 v[126:129], v[144:147], v[176:179], v[126:129]
	v_mfma_f32_16x16x32_bf16 v[126:129], v[148:151], v[184:187], v[126:129]
	v_mfma_f32_16x16x32_bf16 v[122:125], v[156:159], v[184:187], v[122:125]
	v_mfma_f32_16x16x32_bf16 v[122:125], v[152:155], v[176:179], v[122:125]
	v_mfma_f32_16x16x32_bf16 v[106:109], v[152:155], v[180:183], v[106:109]
	v_mfma_f32_16x16x32_bf16 v[106:109], v[156:159], v[216:219], v[106:109]
	v_mfma_f32_16x16x32_bf16 v[110:113], v[148:151], v[216:219], v[110:113]
	v_mfma_f32_16x16x32_bf16 v[110:113], v[144:147], v[180:183], v[110:113]
	v_mfma_f32_16x16x32_bf16 v[94:97], v[144:147], v[220:223], v[94:97]
	v_mfma_f32_16x16x32_bf16 v[94:97], v[148:151], v[230:233], v[94:97]
	v_mfma_f32_16x16x32_bf16 v[90:93], v[156:159], v[230:233], v[90:93]
	v_mfma_f32_16x16x32_bf16 v[90:93], v[152:155], v[220:223], v[90:93]
	v_mfma_f32_16x16x32_bf16 v[74:77], v[152:155], v[224:227], v[74:77]
	v_mfma_f32_16x16x32_bf16 v[74:77], v[156:159], v[234:237], v[74:77]
	v_mfma_f32_16x16x32_bf16 v[78:81], v[148:151], v[234:237], v[78:81]
	v_mfma_f32_16x16x32_bf16 v[78:81], v[144:147], v[224:227], v[78:81]
	s_setprio 0
	s_setprio 3
	v_mfma_f32_16x16x32_bf16 v[118:121], v[160:163], v[176:179], v[118:121]
	v_mfma_f32_16x16x32_bf16 v[118:121], v[164:167], v[184:187], v[118:121]
	v_mfma_f32_16x16x32_bf16 v[114:117], v[172:175], v[184:187], v[114:117]
	v_mfma_f32_16x16x32_bf16 v[114:117], v[168:171], v[176:179], v[114:117]
	v_mfma_f32_16x16x32_bf16 v[98:101], v[168:171], v[180:183], v[98:101]
	v_mfma_f32_16x16x32_bf16 v[98:101], v[172:175], v[216:219], v[98:101]
	v_mfma_f32_16x16x32_bf16 v[102:105], v[164:167], v[216:219], v[102:105]
	v_mfma_f32_16x16x32_bf16 v[102:105], v[160:163], v[180:183], v[102:105]
	v_mfma_f32_16x16x32_bf16 v[86:89], v[160:163], v[220:223], v[86:89]
	v_mfma_f32_16x16x32_bf16 v[86:89], v[164:167], v[230:233], v[86:89]
	v_mfma_f32_16x16x32_bf16 v[82:85], v[172:175], v[230:233], v[82:85]
	v_mfma_f32_16x16x32_bf16 v[82:85], v[168:171], v[220:223], v[82:85]
	v_mfma_f32_16x16x32_bf16 v[66:69], v[168:171], v[224:227], v[66:69]
	v_mfma_f32_16x16x32_bf16 v[66:69], v[172:175], v[234:237], v[66:69]
	v_mfma_f32_16x16x32_bf16 v[70:73], v[164:167], v[234:237], v[70:73]
	v_mfma_f32_16x16x32_bf16 v[70:73], v[160:163], v[224:227], v[70:73]
	s_setprio 0
	s_barrier
; #define PG8_STAGE(bufoff, gbase, voff) do { _Pragma("unroll") for (int _i = 0; _i < 2; ++_i) \
;         __builtin_amdgcn_global_load_lds((const unsigned*)((const char*)(gbase) + (voff)[_i]), (LAS unsigned*)(lds + (bufoff) + ldsw + _i * 8192), 16, 0, 0); } while (0)
; #define PG8_LDA(dst, b, h) do { _Pragma("unroll") for (int m = 0; m < 4; ++m) _Pragma("unroll") for (int k = 0; k < 2; ++k) dst[m][k] = *(const LAS bf16x8*)(lds + PG8_SA(b, h) + aoffk[k] + m * 2048); } while (0)
; #define PG8_WAIT_V(n) asm volatile("s_waitcnt vmcnt(" #n ")" ::: "memory")
; #define PG8_WAIT_L(n) asm volatile("s_waitcnt lgkmcnt(" #n ")" ::: "memory")
; #define PG8_BAR __builtin_amdgcn_s_barrier()
; #define PG8_SCHED __builtin_amdgcn_sched_barrier(0)
;     __device__ __forceinline__ void mid(Acc& acc, const Unit& u, int s, int wr, int wc, int fr, int fq) const {
;         int lo = (wr * 4 + wc) * 8192 + (fq * 16 + fr) * 16; asm volatile("" : "+v"(lo));
;         const unsigned char* gp = gate + ((size_t)(u.pm * 48 + s * 16 + u.pn) << 16) + lo;
;         u32x4 G[8][2];
; #pragma unroll
;         for (int i = 0; i < 8; ++i) { G[i][0] = __builtin_nontemporal_load((const u32x4*)(gp + i * 1024)); G[i][1] = __builtin_nontemporal_load((const u32x4*)(gp + (1 << 20) + i * 1024)); }
; template <class Epi, class Sched, class GemmT>
; __device__ __forceinline__ void gemm_phase(LAS unsigned char* lds, const GemmT& g, const Sched& S, const Epi& E, const int wid) {
;     ...
;                 PG8_LDA(At, 1, 1); PG8_STAGE(PG8_SB(1, 0), b3, vB2); PG8_STAGE(PG8_SB(1, 1), b3 + hB2, vB2); PG8_STAGE(PG8_SA(1, 0), a3, vA2);
;                 PG8_WAIT_V(8); PG8_WAIT_L(0); PG8_BAR; PG8_MMA(1, 0, At, B0); PG8_MMA(1, 1, At, B1); PG8_BAR; PG8_SCHED;
;             }
;             if constexpr (NSEG > 1) { if (sgi + 1 < NSEG) E.mid(acc, cur, sgi, wr, wc, fr, fq); }
;             cs = ns; cA = ns.A; cB = ns.B; hstepA = nhA; hstepB = nhB;
	s_add_i32 s48, s60, s68
	v_lshl_add_u64 v[202:203], v[202:203], 0, s[20:21]
	s_mov_b32 m0, s48
	ds_read_b128 v[138:141], v212 offset:49152
	ds_read_b128 v[176:179], v212 offset:51200
	ds_read_b128 v[180:183], v213 offset:49152
	ds_read_b128 v[184:187], v213 offset:51200
	ds_read_b128 v[216:219], v212 offset:53248
	ds_read_b128 v[220:223], v212 offset:55296
	ds_read_b128 v[224:227], v213 offset:53248
	ds_read_b128 v[230:233], v213 offset:55296
	global_load_lds_dwordx4 v[202:203], off
	v_lshl_add_u64 v[202:203], v[238:239], 0, s[20:21]
	s_add_i32 m0, s48, 0x2000
	s_add_i32 s48, s61, s68
	global_load_lds_dwordx4 v[202:203], off
	v_lshl_add_u64 v[202:203], v[240:241], 0, s[20:21]
	s_mov_b32 m0, s48
	v_lshl_add_u64 v[188:189], v[188:189], 0, s[20:21]
	global_load_lds_dwordx4 v[202:203], off
	v_lshl_add_u64 v[202:203], v[242:243], 0, s[20:21]
	s_add_i32 m0, s48, 0x2000
	s_nop 0
	global_load_lds_dwordx4 v[202:203], off
	s_mov_b32 m0, s54
	s_nop 0
	global_load_lds_dwordx4 v[188:189], off
	v_lshl_add_u64 v[188:189], v[244:245], 0, s[20:21]
	s_mov_b32 m0, s55
	s_nop 0
	global_load_lds_dwordx4 v[188:189], off
	s_waitcnt vmcnt(8)
	s_waitcnt lgkmcnt(0)
	s_barrier
	s_setprio 3
	s_waitcnt lgkmcnt(0)
	v_mfma_f32_16x16x32_bf16 v[62:65], v[144:147], v[138:141], v[62:65]
	v_mfma_f32_16x16x32_bf16 v[62:65], v[148:151], v[180:183], v[62:65]
	v_mfma_f32_16x16x32_bf16 v[58:61], v[156:159], v[180:183], v[58:61]
	v_mfma_f32_16x16x32_bf16 v[58:61], v[152:155], v[138:141], v[58:61]
	v_mfma_f32_16x16x32_bf16 v[42:45], v[152:155], v[176:179], v[42:45]
	v_mfma_f32_16x16x32_bf16 v[42:45], v[156:159], v[184:187], v[42:45]
	v_mfma_f32_16x16x32_bf16 v[46:49], v[148:151], v[184:187], v[46:49]
	v_mfma_f32_16x16x32_bf16 v[46:49], v[144:147], v[176:179], v[46:49]
	v_mfma_f32_16x16x32_bf16 v[30:33], v[144:147], v[216:219], v[30:33]
	v_mfma_f32_16x16x32_bf16 v[30:33], v[148:151], v[224:227], v[30:33]
	v_mfma_f32_16x16x32_bf16 v[22:25], v[156:159], v[224:227], v[22:25]
	v_mfma_f32_16x16x32_bf16 v[22:25], v[152:155], v[216:219], v[22:25]
	v_mfma_f32_16x16x32_bf16 v[6:9], v[152:155], v[220:223], v[6:9]
	v_mfma_f32_16x16x32_bf16 v[6:9], v[156:159], v[230:233], v[6:9]
	v_mfma_f32_16x16x32_bf16 v[14:17], v[148:151], v[230:233], v[14:17]
	v_mfma_f32_16x16x32_bf16 v[14:17], v[144:147], v[220:223], v[14:17]
	s_setprio 0
	s_setprio 3
	v_mfma_f32_16x16x32_bf16 v[54:57], v[160:163], v[138:141], v[54:57]
	v_mfma_f32_16x16x32_bf16 v[54:57], v[164:167], v[180:183], v[54:57]
	v_mfma_f32_16x16x32_bf16 v[50:53], v[172:175], v[180:183], v[50:53]
	v_mfma_f32_16x16x32_bf16 v[50:53], v[168:171], v[138:141], v[50:53]
	v_mfma_f32_16x16x32_bf16 v[34:37], v[168:171], v[176:179], v[34:37]
	v_mfma_f32_16x16x32_bf16 v[34:37], v[172:175], v[184:187], v[34:37]
	v_mfma_f32_16x16x32_bf16 v[38:41], v[164:167], v[184:187], v[38:41]
	v_mfma_f32_16x16x32_bf16 v[38:41], v[160:163], v[176:179], v[38:41]
	v_mfma_f32_16x16x32_bf16 v[26:29], v[160:163], v[216:219], v[26:29]
	v_mfma_f32_16x16x32_bf16 v[26:29], v[164:167], v[224:227], v[26:29]
	v_mfma_f32_16x16x32_bf16 v[18:21], v[172:175], v[224:227], v[18:21]
	v_mfma_f32_16x16x32_bf16 v[18:21], v[168:171], v[216:219], v[18:21]
	v_mfma_f32_16x16x32_bf16 v[2:5], v[168:171], v[220:223], v[2:5]
	v_mfma_f32_16x16x32_bf16 v[2:5], v[172:175], v[230:233], v[2:5]
	v_mfma_f32_16x16x32_bf16 v[10:13], v[164:167], v[230:233], v[10:13]
	v_mfma_f32_16x16x32_bf16 v[10:13], v[160:163], v[220:223], v[10:13]
	s_setprio 0
	s_barrier
	s_add_u32 s56, s56, 0x100
	s_addc_u32 s57, s57, 0
	s_cmp_ge_u32 s90, s42
	s_cbranch_scc0 .LBB0_764
	s_and_b64 vcc, exec, s[52:53]
	s_cbranch_vccz .LBB0_767
	s_lshl_b32 s42, s83, 4
	s_add_i32 s42, s82, s42
	s_ashr_i32 s43, s42, 31
	s_lshl_b64 s[42:43], s[42:43], 16
	v_mov_b32_e32 v130, v210
	s_add_u32 s42, s22, s42
	s_addc_u32 s43, s23, s43
	v_ashrrev_i32_e32 v131, 31, v130
	v_lshl_add_u64 v[130:131], s[42:43], 0, v[130:131]
	v_add_co_u32_e32 v132, vcc, s69, v130
	s_mov_b32 s42, 0x101000
	s_nop 0
	v_addc_co_u32_e32 v133, vcc, 0, v131, vcc
	global_load_dwordx4 v[186:189], v[130:131], off nt
	v_add_co_u32_e32 v134, vcc, s42, v130
	s_movk_i32 s42, 0x1000
	s_nop 0
	v_addc_co_u32_e32 v135, vcc, 0, v131, vcc
	global_load_dwordx4 v[216:219], v[134:135], off offset:-4096 nt
	global_load_dwordx4 v[178:181], v[130:131], off offset:1024 nt
	global_load_dwordx4 v[182:185], v[132:133], off offset:1024 nt
	global_load_dwordx4 v[170:173], v[130:131], off offset:2048 nt
	global_load_dwordx4 v[174:177], v[132:133], off offset:2048 nt
	global_load_dwordx4 v[162:165], v[130:131], off offset:3072 nt
	global_load_dwordx4 v[166:169], v[132:133], off offset:3072 nt
	v_add_co_u32_e32 v130, vcc, s42, v130
	s_waitcnt vmcnt(0)
;     __device__ __forceinline__ void mid(Acc& acc, const Unit& u, int s, int wr, int wc, int fr, int fq) const {
;     ...
;         for (int i = 0; i < 8; ++i) { G[i][0] = __builtin_nontemporal_load((const u32x4*)(gp + i * 1024)); G[i][1] = __builtin_nontemporal_load((const u32x4*)(gp + (1 << 20) + i * 1024)); }
; #pragma unroll
;         for (int i = 0; i < 8; ++i) { const int ai = i >> 2, m = i & 3;
; #pragma unroll
;             for (int bj = 0; bj < 2; ++bj) {
;                 const u32x4 ga = G[i][0], gb = G[i][1];
;                 const u32x2 wa = bj == 0 ? (u32x2){ga.x, ga.y} : (u32x2){ga.z, ga.w}, wb = bj == 0 ? (u32x2){gb.x, gb.y} : (u32x2){gb.z, gb.w};
;                 float fa[8], fb[8]; gate_unpack8(wa, fa); gate_unpack8(wb, fb);
; #pragma unroll
;                 for (int e = 0; e < 8; ++e) fa[e] = fa[e] * __builtin_amdgcn_rcpf(fb[e]);
;                 f32x4& v0 = acc[ai][bj][m][0]; f32x4& v1 = acc[ai][bj][m][1];
;                 v0[0] *= fa[0]; v0[1] *= fa[1]; v0[2] *= fa[2]; v0[3] *= fa[3]; v1[0] *= fa[4]; v1[1] *= fa[5]; v1[2] *= fa[6]; v1[3] *= fa[7]; }
	v_cvt_f32_ubyte0_e32 v0, v216
	v_addc_co_u32_e32 v131, vcc, 0, v131, vcc
	global_load_dwordx4 v[154:157], v[130:131], off nt
	global_load_dwordx4 v[158:161], v[134:135], off nt
	global_load_dwordx4 v[146:149], v[130:131], off offset:1024 nt
	global_load_dwordx4 v[150:153], v[134:135], off offset:1024 nt
	global_load_dwordx4 v[138:141], v[130:131], off offset:2048 nt
	global_load_dwordx4 v[142:145], v[134:135], off offset:2048 nt
	s_nop 0
	global_load_dwordx4 v[130:133], v[130:131], off offset:3072 nt
	s_nop 0
	global_load_dwordx4 v[134:137], v[134:135], off offset:3072 nt
	v_cvt_f32_ubyte1_e32 v203, v216
	v_cvt_f32_ubyte2_e32 v215, v216
	v_cvt_f32_ubyte3_e32 v220, v216
	v_cvt_f32_ubyte0_e32 v221, v217
	v_cvt_f32_ubyte1_e32 v222, v217
	v_cvt_f32_ubyte2_e32 v223, v217
	v_cvt_f32_ubyte3_e32 v224, v217
	v_rcp_iflag_f32_e32 v202, v0
	v_rcp_iflag_f32_e32 v203, v203
	v_rcp_iflag_f32_e32 v216, v215
	v_rcp_iflag_f32_e32 v217, v220
	v_rcp_iflag_f32_e32 v220, v221
	v_rcp_iflag_f32_e32 v221, v222
	v_rcp_iflag_f32_e32 v222, v223
	v_rcp_iflag_f32_e32 v223, v224
	v_cvt_f32_ubyte3_e32 v225, v186
	v_cvt_f32_ubyte2_e32 v224, v186
	v_cvt_f32_ubyte1_e32 v227, v186
	v_cvt_f32_ubyte0_e32 v226, v186
	v_pk_mul_f32 v[202:203], v[202:203], v[226:227]
	v_pk_mul_f32 v[216:217], v[216:217], v[224:225]
	v_pk_mul_f32 v[126:127], v[126:127], v[202:203]
	v_pk_mul_f32 v[128:129], v[128:129], v[216:217]
	v_cvt_f32_ubyte3_e32 v203, v187
	v_cvt_f32_ubyte2_e32 v202, v187
	v_cvt_f32_ubyte1_e32 v217, v187
	v_cvt_f32_ubyte0_e32 v216, v187
	v_pk_mul_f32 v[186:187], v[220:221], v[216:217]
	v_pk_mul_f32 v[202:203], v[222:223], v[202:203]
	v_pk_mul_f32 v[122:123], v[122:123], v[186:187]
	v_pk_mul_f32 v[124:125], v[124:125], v[202:203]
	v_cvt_f32_ubyte0_e32 v0, v218
	v_cvt_f32_ubyte1_e32 v186, v218
	v_cvt_f32_ubyte2_e32 v187, v218
	v_cvt_f32_ubyte3_e32 v202, v218
	v_cvt_f32_ubyte0_e32 v203, v219
	v_cvt_f32_ubyte1_e32 v215, v219
	v_cvt_f32_ubyte2_e32 v220, v219
	v_cvt_f32_ubyte3_e32 v221, v219
	v_rcp_iflag_f32_e32 v216, v0
	v_rcp_iflag_f32_e32 v217, v186
	v_rcp_iflag_f32_e32 v218, v187
	v_rcp_iflag_f32_e32 v219, v202
	v_rcp_iflag_f32_e32 v202, v203
	v_rcp_iflag_f32_e32 v203, v215
	v_rcp_iflag_f32_e32 v186, v220
	v_rcp_iflag_f32_e32 v187, v221
	v_cvt_f32_ubyte3_e32 v221, v188
	v_cvt_f32_ubyte2_e32 v220, v188
	v_cvt_f32_ubyte1_e32 v223, v188
	v_cvt_f32_ubyte0_e32 v222, v188
	v_pk_mul_f32 v[216:217], v[216:217], v[222:223]
	v_pk_mul_f32 v[218:219], v[218:219], v[220:221]
	v_pk_mul_f32 v[118:119], v[118:119], v[216:217]
	v_pk_mul_f32 v[120:121], v[120:121], v[218:219]
	v_cvt_f32_ubyte3_e32 v217, v189
	v_cvt_f32_ubyte2_e32 v216, v189
	v_cvt_f32_ubyte1_e32 v219, v189
	v_cvt_f32_ubyte0_e32 v218, v189
	v_pk_mul_f32 v[188:189], v[202:203], v[218:219]
	v_pk_mul_f32 v[186:187], v[186:187], v[216:217]
	v_pk_mul_f32 v[114:115], v[114:115], v[188:189]
	v_pk_mul_f32 v[116:117], v[116:117], v[186:187]
	v_cvt_f32_ubyte0_e32 v0, v182
	v_cvt_f32_ubyte1_e32 v186, v182
	v_cvt_f32_ubyte2_e32 v187, v182
	v_cvt_f32_ubyte3_e32 v188, v182
	v_cvt_f32_ubyte0_e32 v189, v183
	v_cvt_f32_ubyte1_e32 v202, v183
	v_cvt_f32_ubyte2_e32 v203, v183
	v_cvt_f32_ubyte3_e32 v215, v183
	v_rcp_iflag_f32_e32 v182, v0
	v_rcp_iflag_f32_e32 v183, v186
	v_rcp_iflag_f32_e32 v186, v187
	v_rcp_iflag_f32_e32 v187, v188
	v_rcp_iflag_f32_e32 v188, v189
	v_rcp_iflag_f32_e32 v189, v202
	v_rcp_iflag_f32_e32 v202, v203
	v_rcp_iflag_f32_e32 v203, v215
	v_cvt_f32_ubyte3_e32 v217, v178
	v_cvt_f32_ubyte2_e32 v216, v178
	v_cvt_f32_ubyte1_e32 v219, v178
	v_cvt_f32_ubyte0_e32 v218, v178
	v_pk_mul_f32 v[182:183], v[182:183], v[218:219]
	v_pk_mul_f32 v[186:187], v[186:187], v[216:217]
	v_pk_mul_f32 v[110:111], v[110:111], v[182:183]
	v_pk_mul_f32 v[112:113], v[112:113], v[186:187]
	v_cvt_f32_ubyte3_e32 v183, v179
	v_cvt_f32_ubyte2_e32 v182, v179
	v_cvt_f32_ubyte1_e32 v187, v179
	v_cvt_f32_ubyte0_e32 v186, v179
	v_pk_mul_f32 v[178:179], v[188:189], v[186:187]
	v_pk_mul_f32 v[182:183], v[202:203], v[182:183]
	v_pk_mul_f32 v[106:107], v[106:107], v[178:179]
	v_pk_mul_f32 v[108:109], v[108:109], v[182:183]
	v_cvt_f32_ubyte0_e32 v0, v184
	v_cvt_f32_ubyte1_e32 v179, v184
	v_cvt_f32_ubyte2_e32 v182, v184
	v_cvt_f32_ubyte3_e32 v183, v184
	v_rcp_iflag_f32_e32 v178, v0
	v_rcp_iflag_f32_e32 v179, v179
	v_rcp_iflag_f32_e32 v182, v182
	v_rcp_iflag_f32_e32 v183, v183
	v_cvt_f32_ubyte0_e32 v184, v185
	v_cvt_f32_ubyte1_e32 v186, v185
	v_cvt_f32_ubyte2_e32 v187, v185
	v_cvt_f32_ubyte3_e32 v188, v185
	v_rcp_iflag_f32_e32 v184, v184
	v_rcp_iflag_f32_e32 v185, v186
	v_rcp_iflag_f32_e32 v186, v187
	v_rcp_iflag_f32_e32 v187, v188
	v_cvt_f32_ubyte3_e32 v189, v180
	v_cvt_f32_ubyte2_e32 v188, v180
	v_cvt_f32_ubyte1_e32 v203, v180
	v_cvt_f32_ubyte0_e32 v202, v180
	v_pk_mul_f32 v[178:179], v[178:179], v[202:203]
	v_pk_mul_f32 v[182:183], v[182:183], v[188:189]
	v_pk_mul_f32 v[102:103], v[102:103], v[178:179]
	v_pk_mul_f32 v[104:105], v[104:105], v[182:183]
	v_cvt_f32_ubyte3_e32 v179, v181
	v_cvt_f32_ubyte2_e32 v178, v181
	v_cvt_f32_ubyte1_e32 v183, v181
	v_cvt_f32_ubyte0_e32 v182, v181
	v_pk_mul_f32 v[180:181], v[184:185], v[182:183]
	v_pk_mul_f32 v[178:179], v[186:187], v[178:179]
	v_pk_mul_f32 v[98:99], v[98:99], v[180:181]
	v_pk_mul_f32 v[100:101], v[100:101], v[178:179]
	v_cvt_f32_ubyte0_e32 v0, v174
	v_cvt_f32_ubyte1_e32 v178, v174
	v_cvt_f32_ubyte2_e32 v179, v174
	v_cvt_f32_ubyte3_e32 v180, v174
	v_cvt_f32_ubyte0_e32 v181, v175
	v_cvt_f32_ubyte1_e32 v182, v175
	v_cvt_f32_ubyte2_e32 v183, v175
	v_cvt_f32_ubyte3_e32 v184, v175
	v_rcp_iflag_f32_e32 v174, v0
	v_rcp_iflag_f32_e32 v175, v178
	v_rcp_iflag_f32_e32 v178, v179
	v_rcp_iflag_f32_e32 v179, v180
	v_rcp_iflag_f32_e32 v180, v181
;     __device__ __forceinline__ void mid(Acc& acc, const Unit& u, int s, int wr, int wc, int fr, int fq) const {
;     ...
;         for (int i = 0; i < 8; ++i) { const int ai = i >> 2, m = i & 3;
; #pragma unroll
;             for (int bj = 0; bj < 2; ++bj) {
;                 const u32x4 ga = G[i][0], gb = G[i][1];
;                 const u32x2 wa = bj == 0 ? (u32x2){ga.x, ga.y} : (u32x2){ga.z, ga.w}, wb = bj == 0 ? (u32x2){gb.x, gb.y} : (u32x2){gb.z, gb.w};
;                 float fa[8], fb[8]; gate_unpack8(wa, fa); gate_unpack8(wb, fb);
; #pragma unroll
;                 for (int e = 0; e < 8; ++e) fa[e] = fa[e] * __builtin_amdgcn_rcpf(fb[e]);
;                 f32x4& v0 = acc[ai][bj][m][0]; f32x4& v1 = acc[ai][bj][m][1];
;                 v0[0] *= fa[0]; v0[1] *= fa[1]; v0[2] *= fa[2]; v0[3] *= fa[3]; v1[0] *= fa[4]; v1[1] *= fa[5]; v1[2] *= fa[6]; v1[3] *= fa[7]; }
	v_rcp_iflag_f32_e32 v181, v182
	v_rcp_iflag_f32_e32 v182, v183
	v_rcp_iflag_f32_e32 v183, v184
	v_cvt_f32_ubyte3_e32 v185, v170
	v_cvt_f32_ubyte2_e32 v184, v170
	v_cvt_f32_ubyte1_e32 v187, v170
	v_cvt_f32_ubyte0_e32 v186, v170
	v_pk_mul_f32 v[174:175], v[174:175], v[186:187]
	v_pk_mul_f32 v[178:179], v[178:179], v[184:185]
	v_pk_mul_f32 v[94:95], v[94:95], v[174:175]
	v_pk_mul_f32 v[96:97], v[96:97], v[178:179]
	v_cvt_f32_ubyte3_e32 v175, v171
	v_cvt_f32_ubyte2_e32 v174, v171
	v_cvt_f32_ubyte1_e32 v179, v171
	v_cvt_f32_ubyte0_e32 v178, v171
	v_pk_mul_f32 v[170:171], v[180:181], v[178:179]
	v_pk_mul_f32 v[174:175], v[182:183], v[174:175]
	v_pk_mul_f32 v[90:91], v[90:91], v[170:171]
	v_pk_mul_f32 v[92:93], v[92:93], v[174:175]
	v_cvt_f32_ubyte0_e32 v0, v176
	v_cvt_f32_ubyte1_e32 v171, v176
	v_cvt_f32_ubyte2_e32 v174, v176
	v_cvt_f32_ubyte3_e32 v175, v176
	v_rcp_iflag_f32_e32 v170, v0
	v_rcp_iflag_f32_e32 v171, v171
	v_rcp_iflag_f32_e32 v174, v174
	v_rcp_iflag_f32_e32 v175, v175
	v_cvt_f32_ubyte0_e32 v176, v177
	v_cvt_f32_ubyte1_e32 v178, v177
	v_cvt_f32_ubyte2_e32 v179, v177
	v_cvt_f32_ubyte3_e32 v180, v177
	v_rcp_iflag_f32_e32 v176, v176
	v_rcp_iflag_f32_e32 v177, v178
	v_rcp_iflag_f32_e32 v178, v179
	v_rcp_iflag_f32_e32 v179, v180
	v_cvt_f32_ubyte3_e32 v181, v172
	v_cvt_f32_ubyte2_e32 v180, v172
	v_cvt_f32_ubyte1_e32 v183, v172
	v_cvt_f32_ubyte0_e32 v182, v172
	v_pk_mul_f32 v[170:171], v[170:171], v[182:183]
	v_pk_mul_f32 v[174:175], v[174:175], v[180:181]
	v_pk_mul_f32 v[86:87], v[86:87], v[170:171]
	v_pk_mul_f32 v[88:89], v[88:89], v[174:175]
	v_cvt_f32_ubyte3_e32 v171, v173
	v_cvt_f32_ubyte2_e32 v170, v173
	v_cvt_f32_ubyte1_e32 v175, v173
	v_cvt_f32_ubyte0_e32 v174, v173
	v_pk_mul_f32 v[172:173], v[176:177], v[174:175]
	v_pk_mul_f32 v[170:171], v[178:179], v[170:171]
	v_pk_mul_f32 v[82:83], v[82:83], v[172:173]
	v_pk_mul_f32 v[84:85], v[84:85], v[170:171]
	v_cvt_f32_ubyte0_e32 v0, v166
	v_cvt_f32_ubyte1_e32 v170, v166
	v_cvt_f32_ubyte2_e32 v171, v166
	v_cvt_f32_ubyte3_e32 v172, v166
	v_cvt_f32_ubyte0_e32 v173, v167
	v_cvt_f32_ubyte1_e32 v174, v167
	v_cvt_f32_ubyte2_e32 v175, v167
	v_cvt_f32_ubyte3_e32 v176, v167
	v_rcp_iflag_f32_e32 v166, v0
	v_rcp_iflag_f32_e32 v167, v170
	v_rcp_iflag_f32_e32 v170, v171
	v_rcp_iflag_f32_e32 v171, v172
	v_rcp_iflag_f32_e32 v172, v173
	v_rcp_iflag_f32_e32 v173, v174
	v_rcp_iflag_f32_e32 v174, v175
	v_rcp_iflag_f32_e32 v175, v176
	v_cvt_f32_ubyte3_e32 v177, v162
	v_cvt_f32_ubyte2_e32 v176, v162
	v_cvt_f32_ubyte1_e32 v179, v162
	v_cvt_f32_ubyte0_e32 v178, v162
	v_pk_mul_f32 v[166:167], v[166:167], v[178:179]
	v_pk_mul_f32 v[170:171], v[170:171], v[176:177]
	v_pk_mul_f32 v[78:79], v[78:79], v[166:167]
	v_pk_mul_f32 v[80:81], v[80:81], v[170:171]
	v_cvt_f32_ubyte3_e32 v167, v163
	v_cvt_f32_ubyte2_e32 v166, v163
	v_cvt_f32_ubyte1_e32 v171, v163
	v_cvt_f32_ubyte0_e32 v170, v163
	v_pk_mul_f32 v[162:163], v[172:173], v[170:171]
	v_pk_mul_f32 v[166:167], v[174:175], v[166:167]
	v_pk_mul_f32 v[74:75], v[74:75], v[162:163]
	v_pk_mul_f32 v[76:77], v[76:77], v[166:167]
	v_cvt_f32_ubyte0_e32 v0, v168
	v_cvt_f32_ubyte1_e32 v163, v168
	v_cvt_f32_ubyte2_e32 v166, v168
	v_cvt_f32_ubyte3_e32 v167, v168
	v_rcp_iflag_f32_e32 v162, v0
	v_rcp_iflag_f32_e32 v163, v163
	v_rcp_iflag_f32_e32 v166, v166
	v_rcp_iflag_f32_e32 v167, v167
	v_cvt_f32_ubyte0_e32 v168, v169
	v_cvt_f32_ubyte1_e32 v170, v169
	v_cvt_f32_ubyte2_e32 v171, v169
	v_cvt_f32_ubyte3_e32 v172, v169
	v_rcp_iflag_f32_e32 v168, v168
	v_rcp_iflag_f32_e32 v169, v170
	v_rcp_iflag_f32_e32 v170, v171
	v_rcp_iflag_f32_e32 v171, v172
	v_cvt_f32_ubyte3_e32 v173, v164
	v_cvt_f32_ubyte2_e32 v172, v164
	v_cvt_f32_ubyte1_e32 v175, v164
	v_cvt_f32_ubyte0_e32 v174, v164
	v_pk_mul_f32 v[162:163], v[162:163], v[174:175]
	v_pk_mul_f32 v[166:167], v[166:167], v[172:173]
	v_pk_mul_f32 v[70:71], v[70:71], v[162:163]
	v_pk_mul_f32 v[72:73], v[72:73], v[166:167]
	v_cvt_f32_ubyte3_e32 v163, v165
	v_cvt_f32_ubyte2_e32 v162, v165
	v_cvt_f32_ubyte1_e32 v167, v165
	v_cvt_f32_ubyte0_e32 v166, v165
	v_pk_mul_f32 v[164:165], v[168:169], v[166:167]
	v_pk_mul_f32 v[162:163], v[170:171], v[162:163]
	v_pk_mul_f32 v[66:67], v[66:67], v[164:165]
	v_pk_mul_f32 v[68:69], v[68:69], v[162:163]
	s_waitcnt vmcnt(6)
	v_cvt_f32_ubyte0_e32 v0, v158
	v_cvt_f32_ubyte1_e32 v162, v158
	v_cvt_f32_ubyte2_e32 v163, v158
	v_cvt_f32_ubyte3_e32 v164, v158
	v_cvt_f32_ubyte0_e32 v165, v159
	v_cvt_f32_ubyte1_e32 v166, v159
	v_cvt_f32_ubyte2_e32 v167, v159
	v_cvt_f32_ubyte3_e32 v168, v159
	v_rcp_iflag_f32_e32 v158, v0
	v_rcp_iflag_f32_e32 v159, v162
	v_rcp_iflag_f32_e32 v162, v163
	v_rcp_iflag_f32_e32 v163, v164
	v_rcp_iflag_f32_e32 v164, v165
	v_rcp_iflag_f32_e32 v165, v166
	v_rcp_iflag_f32_e32 v166, v167
	v_rcp_iflag_f32_e32 v167, v168
	v_cvt_f32_ubyte3_e32 v169, v154
	v_cvt_f32_ubyte2_e32 v168, v154
	v_cvt_f32_ubyte1_e32 v171, v154
	v_cvt_f32_ubyte0_e32 v170, v154
	v_pk_mul_f32 v[158:159], v[158:159], v[170:171]
	v_pk_mul_f32 v[162:163], v[162:163], v[168:169]
	v_pk_mul_f32 v[62:63], v[62:63], v[158:159]
	v_pk_mul_f32 v[64:65], v[64:65], v[162:163]
	v_cvt_f32_ubyte3_e32 v159, v155
	v_cvt_f32_ubyte2_e32 v158, v155
	v_cvt_f32_ubyte1_e32 v163, v155
	v_cvt_f32_ubyte0_e32 v162, v155
	v_pk_mul_f32 v[154:155], v[164:165], v[162:163]
	v_pk_mul_f32 v[158:159], v[166:167], v[158:159]
	v_pk_mul_f32 v[58:59], v[58:59], v[154:155]
	v_pk_mul_f32 v[60:61], v[60:61], v[158:159]
	v_cvt_f32_ubyte0_e32 v0, v160
	v_cvt_f32_ubyte1_e32 v155, v160
	v_cvt_f32_ubyte2_e32 v158, v160
	v_cvt_f32_ubyte3_e32 v159, v160
	v_rcp_iflag_f32_e32 v154, v0
	v_rcp_iflag_f32_e32 v155, v155
	v_rcp_iflag_f32_e32 v158, v158
	v_rcp_iflag_f32_e32 v159, v159
	v_cvt_f32_ubyte0_e32 v160, v161
	v_cvt_f32_ubyte1_e32 v162, v161
	v_cvt_f32_ubyte2_e32 v163, v161
	v_cvt_f32_ubyte3_e32 v164, v161
	v_rcp_iflag_f32_e32 v160, v160
	v_rcp_iflag_f32_e32 v161, v162
	v_rcp_iflag_f32_e32 v162, v163
	v_rcp_iflag_f32_e32 v163, v164
	v_cvt_f32_ubyte3_e32 v165, v156
	v_cvt_f32_ubyte2_e32 v164, v156
	v_cvt_f32_ubyte1_e32 v167, v156
	v_cvt_f32_ubyte0_e32 v166, v156
	v_pk_mul_f32 v[154:155], v[154:155], v[166:167]
	v_pk_mul_f32 v[158:159], v[158:159], v[164:165]
	v_pk_mul_f32 v[54:55], v[54:55], v[154:155]
	v_pk_mul_f32 v[56:57], v[56:57], v[158:159]
	v_cvt_f32_ubyte3_e32 v155, v157
	v_cvt_f32_ubyte2_e32 v154, v157
	v_cvt_f32_ubyte1_e32 v159, v157
	v_cvt_f32_ubyte0_e32 v158, v157
	v_pk_mul_f32 v[156:157], v[160:161], v[158:159]
	v_pk_mul_f32 v[154:155], v[162:163], v[154:155]
	v_pk_mul_f32 v[50:51], v[50:51], v[156:157]
	v_pk_mul_f32 v[52:53], v[52:53], v[154:155]
	s_waitcnt vmcnt(4)
;     __device__ __forceinline__ void mid(Acc& acc, const Unit& u, int s, int wr, int wc, int fr, int fq) const {
;     ...
;         for (int i = 0; i < 8; ++i) { const int ai = i >> 2, m = i & 3;
; #pragma unroll
;             for (int bj = 0; bj < 2; ++bj) {
;                 const u32x4 ga = G[i][0], gb = G[i][1];
;                 const u32x2 wa = bj == 0 ? (u32x2){ga.x, ga.y} : (u32x2){ga.z, ga.w}, wb = bj == 0 ? (u32x2){gb.x, gb.y} : (u32x2){gb.z, gb.w};
;                 float fa[8], fb[8]; gate_unpack8(wa, fa); gate_unpack8(wb, fb);
; #pragma unroll
;                 for (int e = 0; e < 8; ++e) fa[e] = fa[e] * __builtin_amdgcn_rcpf(fb[e]);
;                 f32x4& v0 = acc[ai][bj][m][0]; f32x4& v1 = acc[ai][bj][m][1];
;                 v0[0] *= fa[0]; v0[1] *= fa[1]; v0[2] *= fa[2]; v0[3] *= fa[3]; v1[0] *= fa[4]; v1[1] *= fa[5]; v1[2] *= fa[6]; v1[3] *= fa[7]; }
;             __builtin_amdgcn_sched_barrier(0); }
	v_cvt_f32_ubyte0_e32 v0, v150
	v_cvt_f32_ubyte1_e32 v154, v150
	v_cvt_f32_ubyte2_e32 v155, v150
	v_cvt_f32_ubyte3_e32 v156, v150
	v_cvt_f32_ubyte0_e32 v157, v151
	v_cvt_f32_ubyte1_e32 v158, v151
	v_cvt_f32_ubyte2_e32 v159, v151
	v_cvt_f32_ubyte3_e32 v160, v151
	v_rcp_iflag_f32_e32 v150, v0
	v_rcp_iflag_f32_e32 v151, v154
	v_rcp_iflag_f32_e32 v154, v155
	v_rcp_iflag_f32_e32 v155, v156
	v_rcp_iflag_f32_e32 v156, v157
	v_rcp_iflag_f32_e32 v157, v158
	v_rcp_iflag_f32_e32 v158, v159
	v_rcp_iflag_f32_e32 v159, v160
	v_cvt_f32_ubyte3_e32 v161, v146
	v_cvt_f32_ubyte2_e32 v160, v146
	v_cvt_f32_ubyte1_e32 v163, v146
	v_cvt_f32_ubyte0_e32 v162, v146
	v_pk_mul_f32 v[150:151], v[150:151], v[162:163]
	v_pk_mul_f32 v[154:155], v[154:155], v[160:161]
	v_pk_mul_f32 v[46:47], v[46:47], v[150:151]
	v_pk_mul_f32 v[48:49], v[48:49], v[154:155]
	v_cvt_f32_ubyte3_e32 v151, v147
	v_cvt_f32_ubyte2_e32 v150, v147
	v_cvt_f32_ubyte1_e32 v155, v147
	v_cvt_f32_ubyte0_e32 v154, v147
	v_pk_mul_f32 v[146:147], v[156:157], v[154:155]
	v_pk_mul_f32 v[150:151], v[158:159], v[150:151]
	v_pk_mul_f32 v[42:43], v[42:43], v[146:147]
	v_pk_mul_f32 v[44:45], v[44:45], v[150:151]
	v_cvt_f32_ubyte0_e32 v0, v152
	v_cvt_f32_ubyte1_e32 v147, v152
	v_cvt_f32_ubyte2_e32 v150, v152
	v_cvt_f32_ubyte3_e32 v151, v152
	v_rcp_iflag_f32_e32 v146, v0
	v_rcp_iflag_f32_e32 v147, v147
	v_rcp_iflag_f32_e32 v150, v150
	v_rcp_iflag_f32_e32 v151, v151
	v_cvt_f32_ubyte0_e32 v152, v153
	v_cvt_f32_ubyte1_e32 v154, v153
	v_cvt_f32_ubyte2_e32 v155, v153
	v_cvt_f32_ubyte3_e32 v156, v153
	v_rcp_iflag_f32_e32 v152, v152
	v_rcp_iflag_f32_e32 v153, v154
	v_rcp_iflag_f32_e32 v154, v155
	v_rcp_iflag_f32_e32 v155, v156
	v_cvt_f32_ubyte3_e32 v157, v148
	v_cvt_f32_ubyte2_e32 v156, v148
	v_cvt_f32_ubyte1_e32 v159, v148
	v_cvt_f32_ubyte0_e32 v158, v148
	v_pk_mul_f32 v[146:147], v[146:147], v[158:159]
	v_pk_mul_f32 v[150:151], v[150:151], v[156:157]
	v_pk_mul_f32 v[38:39], v[38:39], v[146:147]
	v_pk_mul_f32 v[40:41], v[40:41], v[150:151]
	v_cvt_f32_ubyte3_e32 v147, v149
	v_cvt_f32_ubyte2_e32 v146, v149
	v_cvt_f32_ubyte1_e32 v151, v149
	v_cvt_f32_ubyte0_e32 v150, v149
	v_pk_mul_f32 v[148:149], v[152:153], v[150:151]
	v_pk_mul_f32 v[146:147], v[154:155], v[146:147]
	v_pk_mul_f32 v[34:35], v[34:35], v[148:149]
	v_pk_mul_f32 v[36:37], v[36:37], v[146:147]
	s_waitcnt vmcnt(2)
	v_cvt_f32_ubyte0_e32 v0, v142
	v_cvt_f32_ubyte1_e32 v146, v142
	v_cvt_f32_ubyte2_e32 v147, v142
	v_cvt_f32_ubyte3_e32 v148, v142
	v_cvt_f32_ubyte0_e32 v149, v143
	v_cvt_f32_ubyte1_e32 v150, v143
	v_cvt_f32_ubyte2_e32 v151, v143
	v_cvt_f32_ubyte3_e32 v152, v143
	v_rcp_iflag_f32_e32 v142, v0
	v_rcp_iflag_f32_e32 v143, v146
	v_rcp_iflag_f32_e32 v146, v147
	v_rcp_iflag_f32_e32 v147, v148
	v_rcp_iflag_f32_e32 v148, v149
	v_rcp_iflag_f32_e32 v149, v150
	v_rcp_iflag_f32_e32 v150, v151
	v_rcp_iflag_f32_e32 v151, v152
	v_cvt_f32_ubyte3_e32 v153, v138
	v_cvt_f32_ubyte2_e32 v152, v138
	v_cvt_f32_ubyte1_e32 v155, v138
	v_cvt_f32_ubyte0_e32 v154, v138
	v_pk_mul_f32 v[142:143], v[142:143], v[154:155]
	v_pk_mul_f32 v[146:147], v[146:147], v[152:153]
	v_pk_mul_f32 v[30:31], v[30:31], v[142:143]
	v_pk_mul_f32 v[32:33], v[32:33], v[146:147]
	v_cvt_f32_ubyte3_e32 v143, v139
	v_cvt_f32_ubyte2_e32 v142, v139
	v_cvt_f32_ubyte1_e32 v147, v139
	v_cvt_f32_ubyte0_e32 v146, v139
	v_pk_mul_f32 v[138:139], v[148:149], v[146:147]
	v_pk_mul_f32 v[142:143], v[150:151], v[142:143]
	v_pk_mul_f32 v[22:23], v[22:23], v[138:139]
	v_pk_mul_f32 v[24:25], v[24:25], v[142:143]
	v_cvt_f32_ubyte0_e32 v0, v144
	v_cvt_f32_ubyte1_e32 v139, v144
	v_cvt_f32_ubyte2_e32 v142, v144
	v_cvt_f32_ubyte3_e32 v143, v144
	v_rcp_iflag_f32_e32 v138, v0
	v_rcp_iflag_f32_e32 v139, v139
	v_rcp_iflag_f32_e32 v142, v142
	v_rcp_iflag_f32_e32 v143, v143
	v_cvt_f32_ubyte0_e32 v144, v145
	v_cvt_f32_ubyte1_e32 v146, v145
	v_cvt_f32_ubyte2_e32 v147, v145
	v_cvt_f32_ubyte3_e32 v148, v145
	v_rcp_iflag_f32_e32 v144, v144
	v_rcp_iflag_f32_e32 v145, v146
	v_rcp_iflag_f32_e32 v146, v147
	v_rcp_iflag_f32_e32 v147, v148
	v_cvt_f32_ubyte3_e32 v149, v140
	v_cvt_f32_ubyte2_e32 v148, v140
	v_cvt_f32_ubyte1_e32 v151, v140
	v_cvt_f32_ubyte0_e32 v150, v140
	v_pk_mul_f32 v[138:139], v[138:139], v[150:151]
	v_pk_mul_f32 v[142:143], v[142:143], v[148:149]
	v_pk_mul_f32 v[26:27], v[26:27], v[138:139]
	v_pk_mul_f32 v[28:29], v[28:29], v[142:143]
	v_cvt_f32_ubyte3_e32 v139, v141
	v_cvt_f32_ubyte2_e32 v138, v141
	v_cvt_f32_ubyte1_e32 v143, v141
	v_cvt_f32_ubyte0_e32 v142, v141
	v_pk_mul_f32 v[140:141], v[144:145], v[142:143]
	v_pk_mul_f32 v[138:139], v[146:147], v[138:139]
	v_pk_mul_f32 v[18:19], v[18:19], v[140:141]
	v_pk_mul_f32 v[20:21], v[20:21], v[138:139]
	s_waitcnt vmcnt(0)
	v_cvt_f32_ubyte0_e32 v0, v134
	v_cvt_f32_ubyte1_e32 v138, v134
	v_cvt_f32_ubyte2_e32 v139, v134
	v_cvt_f32_ubyte3_e32 v140, v134
	v_cvt_f32_ubyte0_e32 v141, v135
	v_cvt_f32_ubyte1_e32 v142, v135
	v_cvt_f32_ubyte2_e32 v143, v135
	v_cvt_f32_ubyte3_e32 v144, v135
	v_rcp_iflag_f32_e32 v134, v0
	v_rcp_iflag_f32_e32 v135, v138
	v_rcp_iflag_f32_e32 v138, v139
	v_rcp_iflag_f32_e32 v139, v140
	v_rcp_iflag_f32_e32 v140, v141
	v_rcp_iflag_f32_e32 v141, v142
	v_rcp_iflag_f32_e32 v142, v143
	v_rcp_iflag_f32_e32 v143, v144
	v_cvt_f32_ubyte3_e32 v145, v130
	v_cvt_f32_ubyte2_e32 v144, v130
	v_cvt_f32_ubyte1_e32 v147, v130
	v_cvt_f32_ubyte0_e32 v146, v130
	v_pk_mul_f32 v[134:135], v[134:135], v[146:147]
	v_pk_mul_f32 v[138:139], v[138:139], v[144:145]
	v_pk_mul_f32 v[14:15], v[14:15], v[134:135]
	v_pk_mul_f32 v[16:17], v[16:17], v[138:139]
	v_cvt_f32_ubyte3_e32 v135, v131
	v_cvt_f32_ubyte2_e32 v134, v131
	v_cvt_f32_ubyte1_e32 v139, v131
	v_cvt_f32_ubyte0_e32 v138, v131
	v_pk_mul_f32 v[130:131], v[140:141], v[138:139]
	v_pk_mul_f32 v[134:135], v[142:143], v[134:135]
	v_pk_mul_f32 v[6:7], v[6:7], v[130:131]
	v_pk_mul_f32 v[8:9], v[8:9], v[134:135]
	v_cvt_f32_ubyte0_e32 v0, v136
	v_cvt_f32_ubyte1_e32 v131, v136
	v_cvt_f32_ubyte2_e32 v134, v136
	v_cvt_f32_ubyte3_e32 v135, v136
	v_rcp_iflag_f32_e32 v130, v0
	v_rcp_iflag_f32_e32 v131, v131
	v_rcp_iflag_f32_e32 v134, v134
	v_rcp_iflag_f32_e32 v135, v135
	v_cvt_f32_ubyte0_e32 v136, v137
	v_cvt_f32_ubyte1_e32 v138, v137
	v_cvt_f32_ubyte2_e32 v139, v137
	v_cvt_f32_ubyte3_e32 v140, v137
	v_rcp_iflag_f32_e32 v136, v136
	v_rcp_iflag_f32_e32 v137, v138
	v_rcp_iflag_f32_e32 v138, v139
	v_rcp_iflag_f32_e32 v139, v140
	v_cvt_f32_ubyte3_e32 v141, v132
	v_cvt_f32_ubyte2_e32 v140, v132
	v_cvt_f32_ubyte1_e32 v143, v132
	v_cvt_f32_ubyte0_e32 v142, v132
	v_pk_mul_f32 v[130:131], v[130:131], v[142:143]
	v_pk_mul_f32 v[134:135], v[134:135], v[140:141]
	v_pk_mul_f32 v[10:11], v[10:11], v[130:131]
	v_pk_mul_f32 v[12:13], v[12:13], v[134:135]
	v_cvt_f32_ubyte3_e32 v131, v133
	v_cvt_f32_ubyte2_e32 v130, v133
	v_cvt_f32_ubyte1_e32 v135, v133
	v_cvt_f32_ubyte0_e32 v134, v133
	v_pk_mul_f32 v[132:133], v[136:137], v[134:135]
	v_pk_mul_f32 v[130:131], v[138:139], v[130:131]
	v_pk_mul_f32 v[2:3], v[2:3], v[132:133]
	v_pk_mul_f32 v[4:5], v[4:5], v[130:131]

; #define PG8_STAGE(bufoff, gbase, voff) do { _Pragma("unroll") for (int _i = 0; _i < 2; ++_i) \
;         __builtin_amdgcn_global_load_lds((const unsigned*)((const char*)(gbase) + (voff)[_i]), (LAS unsigned*)(lds + (bufoff) + ldsw + _i * 8192), 16, 0, 0); } while (0)
; #define PG8_LDA(dst, b, h) do { _Pragma("unroll") for (int m = 0; m < 4; ++m) _Pragma("unroll") for (int k = 0; k < 2; ++k) dst[m][k] = *(const LAS bf16x8*)(lds + PG8_SA(b, h) + aoffk[k] + m * 2048); } while (0)
; #define PG8_LDB(dst, b, h) do { _Pragma("unroll") for (int n = 0; n < 2; ++n) _Pragma("unroll") for (int k = 0; k < 2; ++k) dst[n][k] = *(const LAS bf16x8*)(lds + PG8_SB(b, h) + boffk[k] + n * 2048); } while (0)
; #define PG8_WAIT_V(n) asm volatile("s_waitcnt vmcnt(" #n ")" ::: "memory")
; #define PG8_WAIT_L(n) asm volatile("s_waitcnt lgkmcnt(" #n ")" ::: "memory")
; #define PG8_BAR __builtin_amdgcn_s_barrier()
; #define PG8_SCHED __builtin_amdgcn_sched_barrier(0)
; template <class Epi, class Sched, class GemmT>
; __device__ __forceinline__ void gemm_phase(LAS unsigned char* lds, const GemmT& g, const Sched& S, const Epi& E, const int wid) {
;     ...
;             for (int t = 0; t < nt; t += 2) {
;                 const bool last = (t == nt - 2);
;                 const char* a1 = cA + (size_t)(t + 1) * kstep;
;                 const char* a2 = last ? ns.A : cA + (size_t)(t + 2) * kstep; const char* b2 = last ? ns.B : cB + (size_t)(t + 2) * kstep;
;                 const char* a3 = a2 + kstep; const char* b3 = b2 + kstep;
;                 unsigned vA2[2], vB2[2];
; #pragma unroll
;                 for (int i = 0; i < 2; ++i) { vA2[i] = last ? nvA[i] : voffA[i]; vB2[i] = last ? nvB[i] : voffB[i]; }
;                 const size_t hA2 = last ? nhA : hstepA, hB2 = last ? nhB : hstepB;
;                 PG8_LDB(B0, 0, 0); PG8_LDB(B1, 0, 1); PG8_SCHED; PG8_LDA(At, 0, 0); PG8_STAGE(PG8_SA(1, 1), a1 + hstepA, voffA);
;                 PG8_WAIT_V(8); PG8_WAIT_L(0); PG8_BAR; PG8_MMA(0, 0, At, B0); PG8_MMA(0, 1, At, B1); PG8_BAR; PG8_SCHED;
;                 PG8_LDA(At, 0, 1); PG8_STAGE(PG8_SB(0, 0), b2, vB2); PG8_STAGE(PG8_SB(0, 1), b2 + hB2, vB2); PG8_STAGE(PG8_SA(0, 0), a2, vA2);
;                 PG8_WAIT_V(8); PG8_WAIT_L(0); PG8_BAR; PG8_MMA(1, 0, At, B0); PG8_MMA(1, 1, At, B1); PG8_BAR; PG8_SCHED;
.LBB0_846:
	ds_read_b128 v[128:131], v194
	ds_read_b128 v[132:135], v195
	ds_read_b128 v[136:139], v196
	ds_read_b128 v[140:143], v197
	ds_read_b128 v[144:147], v198
	ds_read_b128 v[148:151], v199
	ds_read_b128 v[152:155], v200
	ds_read_b128 v[168:171], v201
	s_add_u32 s44, s42, 0xfff00080
	s_addc_u32 s45, s43, -1
	s_cmp_eq_u32 s62, 60
	s_cselect_b32 s51, s37, s45
	s_cselect_b32 s50, s36, s44
	s_cselect_b32 s45, s59, s61
	s_cselect_b32 s44, s41, s60
	v_lshl_add_u64 v[188:189], s[42:43], 0, v[156:157]
	s_add_i32 m0, s14, 0xc000
	ds_read_b128 v[172:175], v202
	ds_read_b128 v[176:179], v202 offset:2048
	ds_read_b128 v[180:183], v203
	ds_read_b128 v[184:187], v203 offset:2048
	ds_read_b128 v[208:211], v202 offset:4096
	ds_read_b128 v[212:215], v202 offset:6144
	ds_read_b128 v[216:219], v203 offset:4096
	ds_read_b128 v[220:223], v203 offset:6144
	global_load_lds_dwordx4 v[188:189], off
	v_lshl_add_u64 v[188:189], s[42:43], 0, v[160:161]
	s_add_i32 m0, s14, 0xe000
	s_nop 0
	global_load_lds_dwordx4 v[188:189], off
	s_waitcnt vmcnt(8)
	s_waitcnt lgkmcnt(0)
	s_barrier
	s_setprio 3
	s_waitcnt lgkmcnt(0)
	v_mfma_f32_16x16x32_bf16 v[124:127], v[128:131], v[172:175], v[124:127]
	v_mfma_f32_16x16x32_bf16 v[124:127], v[132:135], v[180:183], v[124:127]
	v_mfma_f32_16x16x32_bf16 v[120:123], v[140:143], v[180:183], v[120:123]
	v_mfma_f32_16x16x32_bf16 v[120:123], v[136:139], v[172:175], v[120:123]
	v_mfma_f32_16x16x32_bf16 v[104:107], v[136:139], v[176:179], v[104:107]
	v_mfma_f32_16x16x32_bf16 v[104:107], v[140:143], v[184:187], v[104:107]
	v_mfma_f32_16x16x32_bf16 v[108:111], v[132:135], v[184:187], v[108:111]
	v_mfma_f32_16x16x32_bf16 v[108:111], v[128:131], v[176:179], v[108:111]
	v_mfma_f32_16x16x32_bf16 v[92:95], v[128:131], v[208:211], v[92:95]
	v_mfma_f32_16x16x32_bf16 v[92:95], v[132:135], v[216:219], v[92:95]
	v_mfma_f32_16x16x32_bf16 v[88:91], v[140:143], v[216:219], v[88:91]
	v_mfma_f32_16x16x32_bf16 v[88:91], v[136:139], v[208:211], v[88:91]
	v_mfma_f32_16x16x32_bf16 v[72:75], v[136:139], v[212:215], v[72:75]
	v_mfma_f32_16x16x32_bf16 v[72:75], v[140:143], v[220:223], v[72:75]
	v_mfma_f32_16x16x32_bf16 v[76:79], v[132:135], v[220:223], v[76:79]
	v_mfma_f32_16x16x32_bf16 v[76:79], v[128:131], v[212:215], v[76:79]
	s_setprio 0
	s_setprio 3
	v_mfma_f32_16x16x32_bf16 v[116:119], v[144:147], v[172:175], v[116:119]
	v_mfma_f32_16x16x32_bf16 v[116:119], v[148:151], v[180:183], v[116:119]
	v_mfma_f32_16x16x32_bf16 v[112:115], v[168:171], v[180:183], v[112:115]
	v_mfma_f32_16x16x32_bf16 v[112:115], v[152:155], v[172:175], v[112:115]
	v_mfma_f32_16x16x32_bf16 v[96:99], v[152:155], v[176:179], v[96:99]
	v_mfma_f32_16x16x32_bf16 v[96:99], v[168:171], v[184:187], v[96:99]
	v_mfma_f32_16x16x32_bf16 v[100:103], v[148:151], v[184:187], v[100:103]
	v_mfma_f32_16x16x32_bf16 v[100:103], v[144:147], v[176:179], v[100:103]
	v_mfma_f32_16x16x32_bf16 v[84:87], v[144:147], v[208:211], v[84:87]
	v_mfma_f32_16x16x32_bf16 v[84:87], v[148:151], v[216:219], v[84:87]
	v_mfma_f32_16x16x32_bf16 v[80:83], v[168:171], v[216:219], v[80:83]
	v_mfma_f32_16x16x32_bf16 v[80:83], v[152:155], v[208:211], v[80:83]
	v_mfma_f32_16x16x32_bf16 v[64:67], v[152:155], v[212:215], v[64:67]
	v_mfma_f32_16x16x32_bf16 v[64:67], v[168:171], v[220:223], v[64:67]
	v_mfma_f32_16x16x32_bf16 v[68:71], v[148:151], v[220:223], v[68:71]
	v_mfma_f32_16x16x32_bf16 v[68:71], v[144:147], v[212:215], v[68:71]
	s_setprio 0
	s_barrier
	s_add_i32 s48, s54, s68
	v_lshl_add_u64 v[188:189], s[44:45], 0, v[158:159]
	s_mov_b32 m0, s48
	ds_read_b128 v[172:175], v202 offset:16384
	ds_read_b128 v[176:179], v202 offset:18432
	ds_read_b128 v[180:183], v203 offset:16384
	ds_read_b128 v[184:187], v203 offset:18432
	ds_read_b128 v[208:211], v202 offset:20480
	ds_read_b128 v[212:215], v202 offset:22528
	ds_read_b128 v[216:219], v203 offset:20480
	ds_read_b128 v[220:223], v203 offset:22528
	global_load_lds_dwordx4 v[188:189], off
	s_add_i32 m0, s48, 0x2000
	s_add_u32 s48, s44, 0x100000
	v_lshl_add_u64 v[224:225], s[44:45], 0, v[162:163]
	s_addc_u32 s49, s45, 0
	s_add_i32 s63, s55, s68
	global_load_lds_dwordx4 v[224:225], off
	v_lshl_add_u64 v[226:227], s[48:49], 0, v[158:159]
	s_mov_b32 m0, s63
	v_lshl_add_u64 v[230:231], s[50:51], 0, v[160:161]
	global_load_lds_dwordx4 v[226:227], off
	v_lshl_add_u64 v[226:227], s[48:49], 0, v[162:163]
	s_add_i32 m0, s63, 0x2000
	s_nop 0
	global_load_lds_dwordx4 v[226:227], off
	v_lshl_add_u64 v[226:227], s[50:51], 0, v[156:157]
	s_mov_b32 m0, s14
	s_nop 0
	global_load_lds_dwordx4 v[226:227], off
	s_mov_b32 m0, s15
	s_nop 0
	global_load_lds_dwordx4 v[230:231], off
	s_waitcnt vmcnt(8)
	s_waitcnt lgkmcnt(0)
	s_barrier
; #define PG8_STAGE(bufoff, gbase, voff) do { _Pragma("unroll") for (int _i = 0; _i < 2; ++_i) \
;         __builtin_amdgcn_global_load_lds((const unsigned*)((const char*)(gbase) + (voff)[_i]), (LAS unsigned*)(lds + (bufoff) + ldsw + _i * 8192), 16, 0, 0); } while (0)
; #define PG8_LDA(dst, b, h) do { _Pragma("unroll") for (int m = 0; m < 4; ++m) _Pragma("unroll") for (int k = 0; k < 2; ++k) dst[m][k] = *(const LAS bf16x8*)(lds + PG8_SA(b, h) + aoffk[k] + m * 2048); } while (0)
; #define PG8_LDB(dst, b, h) do { _Pragma("unroll") for (int n = 0; n < 2; ++n) _Pragma("unroll") for (int k = 0; k < 2; ++k) dst[n][k] = *(const LAS bf16x8*)(lds + PG8_SB(b, h) + boffk[k] + n * 2048); } while (0)
; #define PG8_WAIT_V(n) asm volatile("s_waitcnt vmcnt(" #n ")" ::: "memory")
; #define PG8_WAIT_L(n) asm volatile("s_waitcnt lgkmcnt(" #n ")" ::: "memory")
; #define PG8_BAR __builtin_amdgcn_s_barrier()
; #define PG8_SCHED __builtin_amdgcn_sched_barrier(0)
; template <class Epi, class Sched, class GemmT>
; __device__ __forceinline__ void gemm_phase(LAS unsigned char* lds, const GemmT& g, const Sched& S, const Epi& E, const int wid) {
;     ...
;                 PG8_WAIT_V(8); PG8_WAIT_L(0); PG8_BAR; PG8_MMA(1, 0, At, B0); PG8_MMA(1, 1, At, B1); PG8_BAR; PG8_SCHED;
;                 PG8_LDB(B0, 1, 0); PG8_LDB(B1, 1, 1); PG8_SCHED; PG8_LDA(At, 1, 0); PG8_STAGE(PG8_SA(0, 1), a2 + hA2, vA2);
;                 PG8_WAIT_V(8); PG8_WAIT_L(0); PG8_BAR; PG8_MMA(0, 0, At, B0); PG8_MMA(0, 1, At, B1); PG8_BAR; PG8_SCHED;
	s_setprio 3
	s_waitcnt lgkmcnt(0)
	v_mfma_f32_16x16x32_bf16 v[52:55], v[128:131], v[172:175], v[52:55]
	v_mfma_f32_16x16x32_bf16 v[52:55], v[132:135], v[180:183], v[52:55]
	v_mfma_f32_16x16x32_bf16 v[48:51], v[140:143], v[180:183], v[48:51]
	v_mfma_f32_16x16x32_bf16 v[48:51], v[136:139], v[172:175], v[48:51]
	v_mfma_f32_16x16x32_bf16 v[32:35], v[136:139], v[176:179], v[32:35]
	v_mfma_f32_16x16x32_bf16 v[32:35], v[140:143], v[184:187], v[32:35]
	v_mfma_f32_16x16x32_bf16 v[36:39], v[132:135], v[184:187], v[36:39]
	v_mfma_f32_16x16x32_bf16 v[36:39], v[128:131], v[176:179], v[36:39]
	v_mfma_f32_16x16x32_bf16 v[20:23], v[128:131], v[208:211], v[20:23]
	v_mfma_f32_16x16x32_bf16 v[20:23], v[132:135], v[216:219], v[20:23]
	v_mfma_f32_16x16x32_bf16 v[16:19], v[140:143], v[216:219], v[16:19]
	v_mfma_f32_16x16x32_bf16 v[16:19], v[136:139], v[208:211], v[16:19]
	v_mfma_f32_16x16x32_bf16 v[0:3], v[136:139], v[212:215], v[0:3]
	v_mfma_f32_16x16x32_bf16 v[0:3], v[140:143], v[220:223], v[0:3]
	v_mfma_f32_16x16x32_bf16 v[4:7], v[132:135], v[220:223], v[4:7]
	v_mfma_f32_16x16x32_bf16 v[4:7], v[128:131], v[212:215], v[4:7]
	s_setprio 0
	s_setprio 3
	v_mfma_f32_16x16x32_bf16 v[60:63], v[144:147], v[172:175], v[60:63]
	v_mfma_f32_16x16x32_bf16 v[60:63], v[148:151], v[180:183], v[60:63]
	v_mfma_f32_16x16x32_bf16 v[56:59], v[168:171], v[180:183], v[56:59]
	v_mfma_f32_16x16x32_bf16 v[56:59], v[152:155], v[172:175], v[56:59]
	v_mfma_f32_16x16x32_bf16 v[40:43], v[152:155], v[176:179], v[40:43]
	v_mfma_f32_16x16x32_bf16 v[40:43], v[168:171], v[184:187], v[40:43]
	v_mfma_f32_16x16x32_bf16 v[44:47], v[148:151], v[184:187], v[44:47]
	v_mfma_f32_16x16x32_bf16 v[44:47], v[144:147], v[176:179], v[44:47]
	v_mfma_f32_16x16x32_bf16 v[28:31], v[144:147], v[208:211], v[28:31]
	v_mfma_f32_16x16x32_bf16 v[28:31], v[148:151], v[216:219], v[28:31]
	v_mfma_f32_16x16x32_bf16 v[24:27], v[168:171], v[216:219], v[24:27]
	v_mfma_f32_16x16x32_bf16 v[24:27], v[152:155], v[208:211], v[24:27]
	v_mfma_f32_16x16x32_bf16 v[8:11], v[152:155], v[212:215], v[8:11]
	v_mfma_f32_16x16x32_bf16 v[8:11], v[168:171], v[220:223], v[8:11]
	v_mfma_f32_16x16x32_bf16 v[12:15], v[148:151], v[220:223], v[12:15]
	v_mfma_f32_16x16x32_bf16 v[12:15], v[144:147], v[212:215], v[12:15]
	s_setprio 0
	s_barrier
	s_add_i32 s63, 0, 0x18000
	s_add_i32 s64, 0, 0x1c000
	v_add_u32_e32 v128, s63, v191
	v_add_u32_e32 v132, s63, v192
	v_add_u32_e32 v144, s64, v191
	v_add_u32_e32 v148, s64, v192
	ds_read_b128 v[128:131], v128
	ds_read_b128 v[132:135], v132
	ds_read_b128 v[136:139], v204
	ds_read_b128 v[140:143], v205
	ds_read_b128 v[144:147], v144
	ds_read_b128 v[148:151], v148
	ds_read_b128 v[152:155], v206
	ds_read_b128 v[168:171], v207
	s_add_u32 s48, s50, 0x100000
	s_addc_u32 s49, s51, 0
	s_mov_b32 m0, s22
	v_lshl_add_u64 v[232:233], s[48:49], 0, v[156:157]
	ds_read_b128 v[172:175], v202 offset:32768
	ds_read_b128 v[176:179], v202 offset:34816
	ds_read_b128 v[180:183], v203 offset:32768
	ds_read_b128 v[184:187], v203 offset:34816
	ds_read_b128 v[208:211], v202 offset:36864
	ds_read_b128 v[212:215], v202 offset:38912
	ds_read_b128 v[216:219], v203 offset:36864
	ds_read_b128 v[220:223], v203 offset:38912
	global_load_lds_dwordx4 v[232:233], off
	v_lshl_add_u64 v[232:233], s[48:49], 0, v[160:161]
	s_mov_b32 m0, s23
	s_nop 0
	global_load_lds_dwordx4 v[232:233], off
	s_waitcnt vmcnt(8)
	s_waitcnt lgkmcnt(0)
	s_barrier
	s_setprio 3
	s_waitcnt lgkmcnt(0)
	v_mfma_f32_16x16x32_bf16 v[124:127], v[128:131], v[172:175], v[124:127]
	v_mfma_f32_16x16x32_bf16 v[124:127], v[132:135], v[180:183], v[124:127]
	v_mfma_f32_16x16x32_bf16 v[120:123], v[140:143], v[180:183], v[120:123]
	v_mfma_f32_16x16x32_bf16 v[120:123], v[136:139], v[172:175], v[120:123]
	v_mfma_f32_16x16x32_bf16 v[104:107], v[136:139], v[176:179], v[104:107]
	v_mfma_f32_16x16x32_bf16 v[104:107], v[140:143], v[184:187], v[104:107]
	v_mfma_f32_16x16x32_bf16 v[108:111], v[132:135], v[184:187], v[108:111]
	v_mfma_f32_16x16x32_bf16 v[108:111], v[128:131], v[176:179], v[108:111]
	v_mfma_f32_16x16x32_bf16 v[92:95], v[128:131], v[208:211], v[92:95]
	v_mfma_f32_16x16x32_bf16 v[92:95], v[132:135], v[216:219], v[92:95]
	v_mfma_f32_16x16x32_bf16 v[88:91], v[140:143], v[216:219], v[88:91]
	v_mfma_f32_16x16x32_bf16 v[88:91], v[136:139], v[208:211], v[88:91]
	v_mfma_f32_16x16x32_bf16 v[72:75], v[136:139], v[212:215], v[72:75]
	v_mfma_f32_16x16x32_bf16 v[72:75], v[140:143], v[220:223], v[72:75]
	v_mfma_f32_16x16x32_bf16 v[76:79], v[132:135], v[220:223], v[76:79]
	v_mfma_f32_16x16x32_bf16 v[76:79], v[128:131], v[212:215], v[76:79]
	s_setprio 0
	s_setprio 3
	v_mfma_f32_16x16x32_bf16 v[116:119], v[144:147], v[172:175], v[116:119]
	v_mfma_f32_16x16x32_bf16 v[116:119], v[148:151], v[180:183], v[116:119]
	v_mfma_f32_16x16x32_bf16 v[112:115], v[168:171], v[180:183], v[112:115]
	v_mfma_f32_16x16x32_bf16 v[112:115], v[152:155], v[172:175], v[112:115]
	v_mfma_f32_16x16x32_bf16 v[96:99], v[152:155], v[176:179], v[96:99]
	v_mfma_f32_16x16x32_bf16 v[96:99], v[168:171], v[184:187], v[96:99]
	v_mfma_f32_16x16x32_bf16 v[100:103], v[148:151], v[184:187], v[100:103]
	v_mfma_f32_16x16x32_bf16 v[100:103], v[144:147], v[176:179], v[100:103]
	v_mfma_f32_16x16x32_bf16 v[84:87], v[144:147], v[208:211], v[84:87]
	v_mfma_f32_16x16x32_bf16 v[84:87], v[148:151], v[216:219], v[84:87]
	v_mfma_f32_16x16x32_bf16 v[80:83], v[168:171], v[216:219], v[80:83]
	v_mfma_f32_16x16x32_bf16 v[80:83], v[152:155], v[208:211], v[80:83]
	v_mfma_f32_16x16x32_bf16 v[64:67], v[152:155], v[212:215], v[64:67]
	v_mfma_f32_16x16x32_bf16 v[64:67], v[168:171], v[220:223], v[64:67]
	v_mfma_f32_16x16x32_bf16 v[68:71], v[148:151], v[220:223], v[68:71]
	v_mfma_f32_16x16x32_bf16 v[68:71], v[144:147], v[212:215], v[68:71]
	s_setprio 0
	s_barrier
; #define PG8_STAGE(bufoff, gbase, voff) do { _Pragma("unroll") for (int _i = 0; _i < 2; ++_i) \
;         __builtin_amdgcn_global_load_lds((const unsigned*)((const char*)(gbase) + (voff)[_i]), (LAS unsigned*)(lds + (bufoff) + ldsw + _i * 8192), 16, 0, 0); } while (0)
; #define PG8_LDA(dst, b, h) do { _Pragma("unroll") for (int m = 0; m < 4; ++m) _Pragma("unroll") for (int k = 0; k < 2; ++k) dst[m][k] = *(const LAS bf16x8*)(lds + PG8_SA(b, h) + aoffk[k] + m * 2048); } while (0)
; #define PG8_WAIT_V(n) asm volatile("s_waitcnt vmcnt(" #n ")" ::: "memory")
; #define PG8_WAIT_L(n) asm volatile("s_waitcnt lgkmcnt(" #n ")" ::: "memory")
; #define PG8_BAR __builtin_amdgcn_s_barrier()
; #define PG8_SCHED __builtin_amdgcn_sched_barrier(0)
; template <class Epi, class Sched, class GemmT>
; __device__ __forceinline__ void gemm_phase(LAS unsigned char* lds, const GemmT& g, const Sched& S, const Epi& E, const int wid) {
;     ...
;                 PG8_LDA(At, 1, 1); PG8_STAGE(PG8_SB(1, 0), b3, vB2); PG8_STAGE(PG8_SB(1, 1), b3 + hB2, vB2); PG8_STAGE(PG8_SA(1, 0), a3, vA2);
;                 PG8_WAIT_V(8); PG8_WAIT_L(0); PG8_BAR; PG8_MMA(1, 0, At, B0); PG8_MMA(1, 1, At, B1); PG8_BAR; PG8_SCHED;
;             }
	s_add_i32 s48, s63, s68
	v_lshl_add_u64 v[188:189], v[188:189], 0, s[18:19]
	s_mov_b32 m0, s48
	ds_read_b128 v[172:175], v202 offset:49152
	ds_read_b128 v[176:179], v202 offset:51200
	ds_read_b128 v[180:183], v203 offset:49152
	ds_read_b128 v[184:187], v203 offset:51200
	ds_read_b128 v[208:211], v202 offset:53248
	ds_read_b128 v[212:215], v202 offset:55296
	ds_read_b128 v[216:219], v203 offset:53248
	ds_read_b128 v[220:223], v203 offset:55296
	global_load_lds_dwordx4 v[188:189], off
	s_add_i32 m0, s48, 0x2000
	s_add_u32 s44, s44, 0x100080
	v_lshl_add_u64 v[188:189], v[224:225], 0, s[18:19]
	s_addc_u32 s45, s45, 0
	s_add_i32 s48, s64, s68
	global_load_lds_dwordx4 v[188:189], off
	v_lshl_add_u64 v[188:189], s[44:45], 0, v[158:159]
	s_mov_b32 m0, s48
	s_nop 0
	global_load_lds_dwordx4 v[188:189], off
	v_lshl_add_u64 v[188:189], s[44:45], 0, v[162:163]
	s_add_i32 m0, s48, 0x2000
	s_nop 0
	global_load_lds_dwordx4 v[188:189], off
	v_lshl_add_u64 v[188:189], v[226:227], 0, s[18:19]
	s_mov_b32 m0, s34
	s_nop 0
	global_load_lds_dwordx4 v[188:189], off
	v_lshl_add_u64 v[188:189], v[230:231], 0, s[18:19]
	s_mov_b32 m0, s35
	s_nop 0
	global_load_lds_dwordx4 v[188:189], off
	s_waitcnt vmcnt(8)
	s_waitcnt lgkmcnt(0)
	s_barrier
	s_setprio 3
	s_waitcnt lgkmcnt(0)
	v_mfma_f32_16x16x32_bf16 v[52:55], v[128:131], v[172:175], v[52:55]
	v_mfma_f32_16x16x32_bf16 v[52:55], v[132:135], v[180:183], v[52:55]
	v_mfma_f32_16x16x32_bf16 v[48:51], v[140:143], v[180:183], v[48:51]
	v_mfma_f32_16x16x32_bf16 v[48:51], v[136:139], v[172:175], v[48:51]
	v_mfma_f32_16x16x32_bf16 v[32:35], v[136:139], v[176:179], v[32:35]
	v_mfma_f32_16x16x32_bf16 v[32:35], v[140:143], v[184:187], v[32:35]
	v_mfma_f32_16x16x32_bf16 v[36:39], v[132:135], v[184:187], v[36:39]
	v_mfma_f32_16x16x32_bf16 v[36:39], v[128:131], v[176:179], v[36:39]
	v_mfma_f32_16x16x32_bf16 v[20:23], v[128:131], v[208:211], v[20:23]
	v_mfma_f32_16x16x32_bf16 v[20:23], v[132:135], v[216:219], v[20:23]
	v_mfma_f32_16x16x32_bf16 v[16:19], v[140:143], v[216:219], v[16:19]
	v_mfma_f32_16x16x32_bf16 v[16:19], v[136:139], v[208:211], v[16:19]
	v_mfma_f32_16x16x32_bf16 v[0:3], v[136:139], v[212:215], v[0:3]
	v_mfma_f32_16x16x32_bf16 v[0:3], v[140:143], v[220:223], v[0:3]
	v_mfma_f32_16x16x32_bf16 v[4:7], v[132:135], v[220:223], v[4:7]
	v_mfma_f32_16x16x32_bf16 v[4:7], v[128:131], v[212:215], v[4:7]
	s_setprio 0
	s_setprio 3
	v_mfma_f32_16x16x32_bf16 v[60:63], v[144:147], v[172:175], v[60:63]
	v_mfma_f32_16x16x32_bf16 v[60:63], v[148:151], v[180:183], v[60:63]
	v_mfma_f32_16x16x32_bf16 v[56:59], v[168:171], v[180:183], v[56:59]
	v_mfma_f32_16x16x32_bf16 v[56:59], v[152:155], v[172:175], v[56:59]
	v_mfma_f32_16x16x32_bf16 v[40:43], v[152:155], v[176:179], v[40:43]
	v_mfma_f32_16x16x32_bf16 v[40:43], v[168:171], v[184:187], v[40:43]
	v_mfma_f32_16x16x32_bf16 v[44:47], v[148:151], v[184:187], v[44:47]
	v_mfma_f32_16x16x32_bf16 v[44:47], v[144:147], v[176:179], v[44:47]
	v_mfma_f32_16x16x32_bf16 v[28:31], v[144:147], v[208:211], v[28:31]
	v_mfma_f32_16x16x32_bf16 v[28:31], v[148:151], v[216:219], v[28:31]
	v_mfma_f32_16x16x32_bf16 v[24:27], v[168:171], v[216:219], v[24:27]
	v_mfma_f32_16x16x32_bf16 v[24:27], v[152:155], v[208:211], v[24:27]
	v_mfma_f32_16x16x32_bf16 v[8:11], v[152:155], v[212:215], v[8:11]
	v_mfma_f32_16x16x32_bf16 v[8:11], v[168:171], v[220:223], v[8:11]
	v_mfma_f32_16x16x32_bf16 v[12:15], v[148:151], v[220:223], v[12:15]
	v_mfma_f32_16x16x32_bf16 v[12:15], v[144:147], v[212:215], v[12:15]
	s_setprio 0
	s_barrier
	s_add_i32 s62, s62, 2
	s_add_u32 s42, s42, 0x100
	s_addc_u32 s43, s43, 0
	s_add_u32 s60, s60, 0x100
	s_addc_u32 s61, s61, 0
	s_cmp_gt_u32 s62, 61
	s_cbranch_scc0 .LBB0_846
	s_and_b64 vcc, exec, s[20:21]
	s_cbranch_vccz .LBB0_849
	s_barrier

; #define PG8_STAGE(bufoff, gbase, voff) do { _Pragma("unroll") for (int _i = 0; _i < 2; ++_i) \
;         __builtin_amdgcn_global_load_lds((const unsigned*)((const char*)(gbase) + (voff)[_i]), (LAS unsigned*)(lds + (bufoff) + ldsw + _i * 8192), 16, 0, 0); } while (0)
; #define PG8_LDA(dst, b, h) do { _Pragma("unroll") for (int m = 0; m < 4; ++m) _Pragma("unroll") for (int k = 0; k < 2; ++k) dst[m][k] = *(const LAS bf16x8*)(lds + PG8_SA(b, h) + aoffk[k] + m * 2048); } while (0)
; #define PG8_LDB(dst, b, h) do { _Pragma("unroll") for (int n = 0; n < 2; ++n) _Pragma("unroll") for (int k = 0; k < 2; ++k) dst[n][k] = *(const LAS bf16x8*)(lds + PG8_SB(b, h) + boffk[k] + n * 2048); } while (0)
; #define PG8_WAIT_V(n) asm volatile("s_waitcnt vmcnt(" #n ")" ::: "memory")
; #define PG8_WAIT_L(n) asm volatile("s_waitcnt lgkmcnt(" #n ")" ::: "memory")
; #define PG8_BAR __builtin_amdgcn_s_barrier()
; #define PG8_SCHED __builtin_amdgcn_sched_barrier(0)
; template <class Epi, class Sched, class GemmT>
; __device__ __forceinline__ void gemm_phase(LAS unsigned char* lds, const GemmT& g, const Sched& S, const Epi& E, const int wid) {
;     ...
;             for (int t = 0; t < nt; t += 2) {
;                 const bool last = (t == nt - 2);
;                 const char* a1 = cA + (size_t)(t + 1) * kstep;
;                 const char* a2 = last ? ns.A : cA + (size_t)(t + 2) * kstep; const char* b2 = last ? ns.B : cB + (size_t)(t + 2) * kstep;
;                 const char* a3 = a2 + kstep; const char* b3 = b2 + kstep;
;                 unsigned vA2[2], vB2[2];
; #pragma unroll
;                 for (int i = 0; i < 2; ++i) { vA2[i] = last ? nvA[i] : voffA[i]; vB2[i] = last ? nvB[i] : voffB[i]; }
;                 const size_t hA2 = last ? nhA : hstepA, hB2 = last ? nhB : hstepB;
;                 PG8_LDB(B0, 0, 0); PG8_LDB(B1, 0, 1); PG8_SCHED; PG8_LDA(At, 0, 0); PG8_STAGE(PG8_SA(1, 1), a1 + hstepA, voffA);
;                 PG8_WAIT_V(8); PG8_WAIT_L(0); PG8_BAR; PG8_MMA(0, 0, At, B0); PG8_MMA(0, 1, At, B1); PG8_BAR; PG8_SCHED;
;                 PG8_LDA(At, 0, 1); PG8_STAGE(PG8_SB(0, 0), b2, vB2); PG8_STAGE(PG8_SB(0, 1), b2 + hB2, vB2); PG8_STAGE(PG8_SA(0, 0), a2, vA2);
;                 PG8_WAIT_V(8); PG8_WAIT_L(0); PG8_BAR; PG8_MMA(1, 0, At, B0); PG8_MMA(1, 1, At, B1); PG8_BAR; PG8_SCHED;
.LBB0_936:
	ds_read_b128 v[12:15], v223
	ds_read_b128 v[132:135], v224
	ds_read_b128 v[136:139], v225
	ds_read_b128 v[140:143], v226
	ds_read_b128 v[144:147], v227
	ds_read_b128 v[148:151], v229
	ds_read_b128 v[152:155], v230
	ds_read_b128 v[156:159], v231
	s_add_u32 s66, s64, 0xfff00080
	s_addc_u32 s67, s65, -1
	s_cmp_eq_u32 s81, 60
	s_cselect_b32 s71, s57, s67
	s_cselect_b32 s70, s56, s66
	s_cselect_b32 s67, s77, s79
	s_cselect_b32 s66, s63, s78
	v_lshl_add_u64 v[204:205], s[64:65], 0, v[176:177]
	s_add_i32 m0, s14, 0xc000
	ds_read_b128 v[160:163], v232
	ds_read_b128 v[164:167], v232 offset:2048
	ds_read_b128 v[168:171], v233
	ds_read_b128 v[172:175], v233 offset:2048
	ds_read_b128 v[188:191], v232 offset:4096
	ds_read_b128 v[192:195], v232 offset:6144
	ds_read_b128 v[196:199], v233 offset:4096
	ds_read_b128 v[200:203], v233 offset:6144
	global_load_lds_dwordx4 v[204:205], off
	v_lshl_add_u64 v[204:205], s[64:65], 0, v[180:181]
	s_add_i32 m0, s14, 0xe000
	s_nop 0
	global_load_lds_dwordx4 v[204:205], off
	s_waitcnt vmcnt(8)
	s_waitcnt lgkmcnt(0)
	s_barrier
	s_setprio 3
	s_waitcnt lgkmcnt(0)
	v_mfma_f32_16x16x32_bf16 v[124:127], v[12:15], v[160:163], v[124:127]
	v_mfma_f32_16x16x32_bf16 v[124:127], v[132:135], v[168:171], v[124:127]
	v_mfma_f32_16x16x32_bf16 v[120:123], v[140:143], v[168:171], v[120:123]
	v_mfma_f32_16x16x32_bf16 v[120:123], v[136:139], v[160:163], v[120:123]
	v_mfma_f32_16x16x32_bf16 v[104:107], v[136:139], v[164:167], v[104:107]
	v_mfma_f32_16x16x32_bf16 v[104:107], v[140:143], v[172:175], v[104:107]
	v_mfma_f32_16x16x32_bf16 v[40:43], v[132:135], v[172:175], v[40:43]
	v_mfma_f32_16x16x32_bf16 v[40:43], v[12:15], v[164:167], v[40:43]
	v_mfma_f32_16x16x32_bf16 v[32:35], v[12:15], v[188:191], v[32:35]
	v_mfma_f32_16x16x32_bf16 v[32:35], v[132:135], v[196:199], v[32:35]
	v_mfma_f32_16x16x32_bf16 v[96:99], v[140:143], v[196:199], v[96:99]
	v_mfma_f32_16x16x32_bf16 v[96:99], v[136:139], v[188:191], v[96:99]
	v_mfma_f32_16x16x32_bf16 v[92:95], v[136:139], v[192:195], v[92:95]
	v_mfma_f32_16x16x32_bf16 v[92:95], v[140:143], v[200:203], v[92:95]
	v_mfma_f32_16x16x32_bf16 v[112:115], v[132:135], v[200:203], v[112:115]
	v_mfma_f32_16x16x32_bf16 v[112:115], v[12:15], v[192:195], v[112:115]
	s_setprio 0
	s_setprio 3
	v_mfma_f32_16x16x32_bf16 v[68:71], v[144:147], v[160:163], v[68:71]
	v_mfma_f32_16x16x32_bf16 v[68:71], v[148:151], v[168:171], v[68:71]
	v_mfma_f32_16x16x32_bf16 v[60:63], v[156:159], v[168:171], v[60:63]
	v_mfma_f32_16x16x32_bf16 v[60:63], v[152:155], v[160:163], v[60:63]
	v_mfma_f32_16x16x32_bf16 v[20:23], v[152:155], v[164:167], v[20:23]
	v_mfma_f32_16x16x32_bf16 v[20:23], v[156:159], v[172:175], v[20:23]
	v_mfma_f32_16x16x32_bf16 v[76:79], v[148:151], v[172:175], v[76:79]
	v_mfma_f32_16x16x32_bf16 v[76:79], v[144:147], v[164:167], v[76:79]
	v_mfma_f32_16x16x32_bf16 v[72:75], v[144:147], v[188:191], v[72:75]
	v_mfma_f32_16x16x32_bf16 v[72:75], v[148:151], v[196:199], v[72:75]
	v_mfma_f32_16x16x32_bf16 v[16:19], v[156:159], v[196:199], v[16:19]
	v_mfma_f32_16x16x32_bf16 v[16:19], v[152:155], v[188:191], v[16:19]
	v_mfma_f32_16x16x32_bf16 v[80:83], v[152:155], v[192:195], v[80:83]
	v_mfma_f32_16x16x32_bf16 v[80:83], v[156:159], v[200:203], v[80:83]
	v_mfma_f32_16x16x32_bf16 v[84:87], v[148:151], v[200:203], v[84:87]
	v_mfma_f32_16x16x32_bf16 v[84:87], v[144:147], v[192:195], v[84:87]
	s_setprio 0
	s_barrier
	s_add_i32 s80, s69, s68
	v_lshl_add_u64 v[204:205], s[66:67], 0, v[178:179]
	s_mov_b32 m0, s80
	ds_read_b128 v[160:163], v232 offset:16384
	ds_read_b128 v[164:167], v232 offset:18432
	ds_read_b128 v[168:171], v233 offset:16384
	ds_read_b128 v[172:175], v233 offset:18432
	ds_read_b128 v[188:191], v232 offset:20480
	ds_read_b128 v[192:195], v232 offset:22528
	ds_read_b128 v[196:199], v233 offset:20480
	ds_read_b128 v[200:203], v233 offset:22528
	global_load_lds_dwordx4 v[204:205], off
	s_add_i32 m0, s80, 0x2000
	s_add_u32 s82, s66, 0x100000
	v_lshl_add_u64 v[206:207], s[66:67], 0, v[182:183]
	s_addc_u32 s83, s67, 0
	s_add_i32 s80, s72, s68
	global_load_lds_dwordx4 v[206:207], off
	v_lshl_add_u64 v[240:241], s[82:83], 0, v[178:179]
	s_mov_b32 m0, s80
	v_lshl_add_u64 v[242:243], s[70:71], 0, v[180:181]
	global_load_lds_dwordx4 v[240:241], off
	v_lshl_add_u64 v[240:241], s[82:83], 0, v[182:183]
	s_add_i32 m0, s80, 0x2000
	s_nop 0
	global_load_lds_dwordx4 v[240:241], off
	v_lshl_add_u64 v[240:241], s[70:71], 0, v[176:177]
	s_mov_b32 m0, s14
	s_nop 0
	global_load_lds_dwordx4 v[240:241], off
	s_mov_b32 m0, s15
	s_nop 0
	global_load_lds_dwordx4 v[242:243], off
	s_waitcnt vmcnt(8)
	s_waitcnt lgkmcnt(0)
	s_barrier
; #define PG8_STAGE(bufoff, gbase, voff) do { _Pragma("unroll") for (int _i = 0; _i < 2; ++_i) \
;         __builtin_amdgcn_global_load_lds((const unsigned*)((const char*)(gbase) + (voff)[_i]), (LAS unsigned*)(lds + (bufoff) + ldsw + _i * 8192), 16, 0, 0); } while (0)
; #define PG8_LDA(dst, b, h) do { _Pragma("unroll") for (int m = 0; m < 4; ++m) _Pragma("unroll") for (int k = 0; k < 2; ++k) dst[m][k] = *(const LAS bf16x8*)(lds + PG8_SA(b, h) + aoffk[k] + m * 2048); } while (0)
; #define PG8_LDB(dst, b, h) do { _Pragma("unroll") for (int n = 0; n < 2; ++n) _Pragma("unroll") for (int k = 0; k < 2; ++k) dst[n][k] = *(const LAS bf16x8*)(lds + PG8_SB(b, h) + boffk[k] + n * 2048); } while (0)
; #define PG8_WAIT_V(n) asm volatile("s_waitcnt vmcnt(" #n ")" ::: "memory")
; #define PG8_WAIT_L(n) asm volatile("s_waitcnt lgkmcnt(" #n ")" ::: "memory")
; #define PG8_BAR __builtin_amdgcn_s_barrier()
; #define PG8_SCHED __builtin_amdgcn_sched_barrier(0)
; template <class Epi, class Sched, class GemmT>
; __device__ __forceinline__ void gemm_phase(LAS unsigned char* lds, const GemmT& g, const Sched& S, const Epi& E, const int wid) {
;     ...
;                 PG8_WAIT_V(8); PG8_WAIT_L(0); PG8_BAR; PG8_MMA(1, 0, At, B0); PG8_MMA(1, 1, At, B1); PG8_BAR; PG8_SCHED;
;                 PG8_LDB(B0, 1, 0); PG8_LDB(B1, 1, 1); PG8_SCHED; PG8_LDA(At, 1, 0); PG8_STAGE(PG8_SA(0, 1), a2 + hA2, vA2);
;                 PG8_WAIT_V(8); PG8_WAIT_L(0); PG8_BAR; PG8_MMA(0, 0, At, B0); PG8_MMA(0, 1, At, B1); PG8_BAR; PG8_SCHED;
	s_setprio 3
	s_waitcnt lgkmcnt(0)
	v_mfma_f32_16x16x32_bf16 v[56:59], v[12:15], v[160:163], v[56:59]
	v_mfma_f32_16x16x32_bf16 v[56:59], v[132:135], v[168:171], v[56:59]
	v_mfma_f32_16x16x32_bf16 v[108:111], v[136:139], v[160:163], v[108:111]
	v_mfma_f32_16x16x32_bf16 v[108:111], v[140:143], v[168:171], v[108:111]
	v_mfma_f32_16x16x32_bf16 v[36:39], v[12:15], v[164:167], v[36:39]
	v_mfma_f32_16x16x32_bf16 v[36:39], v[132:135], v[172:175], v[36:39]
	v_mfma_f32_16x16x32_bf16 v[100:103], v[136:139], v[164:167], v[100:103]
	v_mfma_f32_16x16x32_bf16 v[100:103], v[140:143], v[172:175], v[100:103]
	v_mfma_f32_16x16x32_bf16 v[28:31], v[12:15], v[188:191], v[28:31]
	v_mfma_f32_16x16x32_bf16 v[28:31], v[132:135], v[196:199], v[28:31]
	v_mfma_f32_16x16x32_bf16 v[88:91], v[136:139], v[188:191], v[88:91]
	v_mfma_f32_16x16x32_bf16 v[88:91], v[140:143], v[196:199], v[88:91]
	v_mfma_f32_16x16x32_bf16 v[24:27], v[136:139], v[192:195], v[24:27]
	v_mfma_f32_16x16x32_bf16 v[24:27], v[140:143], v[200:203], v[24:27]
	v_mfma_f32_16x16x32_bf16 v[12:15], v[12:15], v[192:195], v[64:67]
	v_mfma_f32_16x16x32_bf16 v[12:15], v[132:135], v[200:203], v[12:15]
	s_setprio 0
	s_setprio 3
	v_mfma_f32_16x16x32_bf16 v[64:67], v[144:147], v[192:195], v[116:119]
	v_mfma_f32_16x16x32_bf16 v[116:119], v[148:151], v[200:203], v[64:67]
	v_mfma_f32_16x16x32_bf16 v[44:47], v[144:147], v[160:163], v[44:47]
	v_mfma_f32_16x16x32_bf16 v[44:47], v[148:151], v[168:171], v[44:47]
	v_mfma_f32_16x16x32_bf16 v[0:3], v[152:155], v[160:163], v[0:3]
	v_mfma_f32_16x16x32_bf16 v[0:3], v[156:159], v[168:171], v[0:3]
	v_mfma_f32_16x16x32_bf16 v[48:51], v[144:147], v[164:167], v[48:51]
	v_mfma_f32_16x16x32_bf16 v[48:51], v[148:151], v[172:175], v[48:51]
	v_mfma_f32_16x16x32_bf16 v[4:7], v[152:155], v[164:167], v[4:7]
	v_mfma_f32_16x16x32_bf16 v[4:7], v[156:159], v[172:175], v[4:7]
	v_mfma_f32_16x16x32_bf16 v[64:67], v[152:155], v[192:195], v[128:131]
	v_mfma_f32_16x16x32_bf16 v[128:131], v[156:159], v[200:203], v[64:67]
	v_mfma_f32_16x16x32_bf16 v[52:55], v[144:147], v[188:191], v[52:55]
	v_mfma_f32_16x16x32_bf16 v[52:55], v[148:151], v[196:199], v[52:55]
	v_mfma_f32_16x16x32_bf16 v[8:11], v[152:155], v[188:191], v[8:11]
	v_mfma_f32_16x16x32_bf16 v[8:11], v[156:159], v[196:199], v[8:11]
	s_setprio 0
	s_barrier
	s_add_i32 s80, 0, 0x18000
	s_add_i32 s82, 0, 0x1c000
	v_add_u32_e32 v64, s80, v210
	v_add_u32_e32 v132, s80, v211
	v_add_u32_e32 v144, s82, v210
	v_add_u32_e32 v148, s82, v211
	ds_read_b128 v[64:67], v64
	ds_read_b128 v[132:135], v132
	ds_read_b128 v[136:139], v234
	ds_read_b128 v[140:143], v235
	ds_read_b128 v[144:147], v144
	ds_read_b128 v[148:151], v148
	ds_read_b128 v[152:155], v236
	ds_read_b128 v[156:159], v237
	s_add_u32 s70, s70, 0x100000
	s_addc_u32 s71, s71, 0
	s_mov_b32 m0, s23
	v_lshl_add_u64 v[244:245], s[70:71], 0, v[176:177]
	ds_read_b128 v[160:163], v232 offset:32768
	ds_read_b128 v[164:167], v232 offset:34816
	ds_read_b128 v[168:171], v233 offset:32768
	ds_read_b128 v[172:175], v233 offset:34816
	ds_read_b128 v[188:191], v232 offset:36864
	ds_read_b128 v[192:195], v232 offset:38912
	ds_read_b128 v[196:199], v233 offset:36864
	ds_read_b128 v[200:203], v233 offset:38912
	global_load_lds_dwordx4 v[244:245], off
	v_lshl_add_u64 v[244:245], s[70:71], 0, v[180:181]
	s_mov_b32 m0, s34
	s_nop 0
	global_load_lds_dwordx4 v[244:245], off
	s_waitcnt vmcnt(8)
	s_waitcnt lgkmcnt(0)
	s_barrier
	s_setprio 3
	s_waitcnt lgkmcnt(0)
	v_mfma_f32_16x16x32_bf16 v[124:127], v[64:67], v[160:163], v[124:127]
	v_mfma_f32_16x16x32_bf16 v[124:127], v[132:135], v[168:171], v[124:127]
	v_mfma_f32_16x16x32_bf16 v[120:123], v[140:143], v[168:171], v[120:123]
	v_mfma_f32_16x16x32_bf16 v[120:123], v[136:139], v[160:163], v[120:123]
	v_mfma_f32_16x16x32_bf16 v[104:107], v[136:139], v[164:167], v[104:107]
	v_mfma_f32_16x16x32_bf16 v[104:107], v[140:143], v[172:175], v[104:107]
	v_mfma_f32_16x16x32_bf16 v[40:43], v[132:135], v[172:175], v[40:43]
	v_mfma_f32_16x16x32_bf16 v[40:43], v[64:67], v[164:167], v[40:43]
	v_mfma_f32_16x16x32_bf16 v[32:35], v[64:67], v[188:191], v[32:35]
	v_mfma_f32_16x16x32_bf16 v[32:35], v[132:135], v[196:199], v[32:35]
	v_mfma_f32_16x16x32_bf16 v[96:99], v[140:143], v[196:199], v[96:99]
	v_mfma_f32_16x16x32_bf16 v[96:99], v[136:139], v[188:191], v[96:99]
	v_mfma_f32_16x16x32_bf16 v[92:95], v[136:139], v[192:195], v[92:95]
	v_mfma_f32_16x16x32_bf16 v[92:95], v[140:143], v[200:203], v[92:95]
	v_mfma_f32_16x16x32_bf16 v[112:115], v[132:135], v[200:203], v[112:115]
	v_mfma_f32_16x16x32_bf16 v[112:115], v[64:67], v[192:195], v[112:115]
	s_setprio 0
	s_setprio 3
	v_mfma_f32_16x16x32_bf16 v[68:71], v[144:147], v[160:163], v[68:71]
	v_mfma_f32_16x16x32_bf16 v[68:71], v[148:151], v[168:171], v[68:71]
	v_mfma_f32_16x16x32_bf16 v[60:63], v[156:159], v[168:171], v[60:63]
	v_mfma_f32_16x16x32_bf16 v[60:63], v[152:155], v[160:163], v[60:63]
	v_mfma_f32_16x16x32_bf16 v[20:23], v[152:155], v[164:167], v[20:23]
	v_mfma_f32_16x16x32_bf16 v[20:23], v[156:159], v[172:175], v[20:23]
	v_mfma_f32_16x16x32_bf16 v[76:79], v[148:151], v[172:175], v[76:79]
	v_mfma_f32_16x16x32_bf16 v[76:79], v[144:147], v[164:167], v[76:79]
	v_mfma_f32_16x16x32_bf16 v[72:75], v[144:147], v[188:191], v[72:75]
	v_mfma_f32_16x16x32_bf16 v[72:75], v[148:151], v[196:199], v[72:75]
	v_mfma_f32_16x16x32_bf16 v[16:19], v[156:159], v[196:199], v[16:19]
	v_mfma_f32_16x16x32_bf16 v[16:19], v[152:155], v[188:191], v[16:19]
	v_mfma_f32_16x16x32_bf16 v[80:83], v[152:155], v[192:195], v[80:83]
	v_mfma_f32_16x16x32_bf16 v[80:83], v[156:159], v[200:203], v[80:83]
	v_mfma_f32_16x16x32_bf16 v[84:87], v[148:151], v[200:203], v[84:87]
	v_mfma_f32_16x16x32_bf16 v[84:87], v[144:147], v[192:195], v[84:87]
	s_setprio 0
	s_barrier
; #define PG8_STAGE(bufoff, gbase, voff) do { _Pragma("unroll") for (int _i = 0; _i < 2; ++_i) \
;         __builtin_amdgcn_global_load_lds((const unsigned*)((const char*)(gbase) + (voff)[_i]), (LAS unsigned*)(lds + (bufoff) + ldsw + _i * 8192), 16, 0, 0); } while (0)
; #define PG8_LDA(dst, b, h) do { _Pragma("unroll") for (int m = 0; m < 4; ++m) _Pragma("unroll") for (int k = 0; k < 2; ++k) dst[m][k] = *(const LAS bf16x8*)(lds + PG8_SA(b, h) + aoffk[k] + m * 2048); } while (0)
; #define PG8_WAIT_V(n) asm volatile("s_waitcnt vmcnt(" #n ")" ::: "memory")
; #define PG8_WAIT_L(n) asm volatile("s_waitcnt lgkmcnt(" #n ")" ::: "memory")
; #define PG8_BAR __builtin_amdgcn_s_barrier()
; #define PG8_SCHED __builtin_amdgcn_sched_barrier(0)
; template <class Epi, class Sched, class GemmT>
; __device__ __forceinline__ void gemm_phase(LAS unsigned char* lds, const GemmT& g, const Sched& S, const Epi& E, const int wid) {
;     ...
;                 PG8_LDA(At, 1, 1); PG8_STAGE(PG8_SB(1, 0), b3, vB2); PG8_STAGE(PG8_SB(1, 1), b3 + hB2, vB2); PG8_STAGE(PG8_SA(1, 0), a3, vA2);
;                 PG8_WAIT_V(8); PG8_WAIT_L(0); PG8_BAR; PG8_MMA(1, 0, At, B0); PG8_MMA(1, 1, At, B1); PG8_BAR; PG8_SCHED;
;             }
	s_add_i32 s70, s80, s68
	v_lshl_add_u64 v[204:205], v[204:205], 0, s[38:39]
	s_mov_b32 m0, s70
	ds_read_b128 v[160:163], v232 offset:49152
	ds_read_b128 v[164:167], v232 offset:51200
	ds_read_b128 v[168:171], v233 offset:49152
	ds_read_b128 v[172:175], v233 offset:51200
	ds_read_b128 v[188:191], v232 offset:53248
	ds_read_b128 v[192:195], v232 offset:55296
	ds_read_b128 v[196:199], v233 offset:53248
	ds_read_b128 v[200:203], v233 offset:55296
	global_load_lds_dwordx4 v[204:205], off
	s_add_i32 m0, s70, 0x2000
	s_add_u32 s66, s66, 0x100080
	v_lshl_add_u64 v[204:205], v[206:207], 0, s[38:39]
	s_addc_u32 s67, s67, 0
	s_add_i32 s70, s82, s68
	global_load_lds_dwordx4 v[204:205], off
	v_lshl_add_u64 v[204:205], s[66:67], 0, v[178:179]
	s_mov_b32 m0, s70
	s_nop 0
	global_load_lds_dwordx4 v[204:205], off
	v_lshl_add_u64 v[204:205], s[66:67], 0, v[182:183]
	s_add_i32 m0, s70, 0x2000
	s_nop 0
	global_load_lds_dwordx4 v[204:205], off
	v_lshl_add_u64 v[204:205], v[240:241], 0, s[38:39]
	s_mov_b32 m0, s54
	s_nop 0
	global_load_lds_dwordx4 v[204:205], off
	v_lshl_add_u64 v[204:205], v[242:243], 0, s[38:39]
	s_mov_b32 m0, s55
	s_nop 0
	global_load_lds_dwordx4 v[204:205], off
	s_waitcnt vmcnt(8)
	s_waitcnt lgkmcnt(0)
	s_barrier
	s_setprio 3
	s_waitcnt lgkmcnt(0)
	v_mfma_f32_16x16x32_bf16 v[12:15], v[64:67], v[192:195], v[12:15]
	v_mfma_f32_16x16x32_bf16 v[56:59], v[64:67], v[160:163], v[56:59]
	v_mfma_f32_16x16x32_bf16 v[56:59], v[132:135], v[168:171], v[56:59]
	v_mfma_f32_16x16x32_bf16 v[108:111], v[136:139], v[160:163], v[108:111]
	v_mfma_f32_16x16x32_bf16 v[108:111], v[140:143], v[168:171], v[108:111]
	v_mfma_f32_16x16x32_bf16 v[36:39], v[64:67], v[164:167], v[36:39]
	v_mfma_f32_16x16x32_bf16 v[36:39], v[132:135], v[172:175], v[36:39]
	v_mfma_f32_16x16x32_bf16 v[100:103], v[136:139], v[164:167], v[100:103]
	v_mfma_f32_16x16x32_bf16 v[100:103], v[140:143], v[172:175], v[100:103]
	v_mfma_f32_16x16x32_bf16 v[28:31], v[64:67], v[188:191], v[28:31]
	v_mfma_f32_16x16x32_bf16 v[28:31], v[132:135], v[196:199], v[28:31]
	v_mfma_f32_16x16x32_bf16 v[88:91], v[136:139], v[188:191], v[88:91]
	v_mfma_f32_16x16x32_bf16 v[88:91], v[140:143], v[196:199], v[88:91]
	v_mfma_f32_16x16x32_bf16 v[64:67], v[132:135], v[200:203], v[12:15]
	v_mfma_f32_16x16x32_bf16 v[12:15], v[136:139], v[192:195], v[24:27]
	v_mfma_f32_16x16x32_bf16 v[24:27], v[140:143], v[200:203], v[12:15]
	s_setprio 0
	s_setprio 3
	v_mfma_f32_16x16x32_bf16 v[12:15], v[144:147], v[160:163], v[44:47]
	v_mfma_f32_16x16x32_bf16 v[44:47], v[148:151], v[168:171], v[12:15]
	v_mfma_f32_16x16x32_bf16 v[0:3], v[152:155], v[160:163], v[0:3]
	v_mfma_f32_16x16x32_bf16 v[0:3], v[156:159], v[168:171], v[0:3]
	v_mfma_f32_16x16x32_bf16 v[4:7], v[152:155], v[164:167], v[4:7]
	v_mfma_f32_16x16x32_bf16 v[4:7], v[156:159], v[172:175], v[4:7]
	v_mfma_f32_16x16x32_bf16 v[12:15], v[144:147], v[164:167], v[48:51]
	v_mfma_f32_16x16x32_bf16 v[48:51], v[148:151], v[172:175], v[12:15]
	v_mfma_f32_16x16x32_bf16 v[8:11], v[152:155], v[188:191], v[8:11]
	v_mfma_f32_16x16x32_bf16 v[8:11], v[156:159], v[196:199], v[8:11]
	v_mfma_f32_16x16x32_bf16 v[12:15], v[144:147], v[188:191], v[52:55]
	v_mfma_f32_16x16x32_bf16 v[52:55], v[148:151], v[196:199], v[12:15]
	v_mfma_f32_16x16x32_bf16 v[12:15], v[144:147], v[192:195], v[116:119]
	v_mfma_f32_16x16x32_bf16 v[116:119], v[148:151], v[200:203], v[12:15]
	v_mfma_f32_16x16x32_bf16 v[12:15], v[152:155], v[192:195], v[128:131]
	v_mfma_f32_16x16x32_bf16 v[128:131], v[156:159], v[200:203], v[12:15]
	s_setprio 0
	s_barrier
	s_add_i32 s81, s81, 2
	s_add_u32 s64, s64, 0x100
	s_addc_u32 s65, s65, 0
	s_add_u32 s78, s78, 0x100
	s_addc_u32 s79, s79, 0
	s_cmp_gt_u32 s81, 61
	s_cbranch_scc0 .LBB0_936
	s_and_b64 vcc, exec, s[40:41]
	s_cbranch_vccz .LBB0_939
	s_barrier

; #define PG8_STAGE(bufoff, gbase, voff) do { _Pragma("unroll") for (int _i = 0; _i < 2; ++_i) \
;         __builtin_amdgcn_global_load_lds((const unsigned*)((const char*)(gbase) + (voff)[_i]), (LAS unsigned*)(lds + (bufoff) + ldsw + _i * 8192), 16, 0, 0); } while (0)
; #define PG8_LDA(dst, b, h) do { _Pragma("unroll") for (int m = 0; m < 4; ++m) _Pragma("unroll") for (int k = 0; k < 2; ++k) dst[m][k] = *(const LAS bf16x8*)(lds + PG8_SA(b, h) + aoffk[k] + m * 2048); } while (0)
; #define PG8_LDB(dst, b, h) do { _Pragma("unroll") for (int n = 0; n < 2; ++n) _Pragma("unroll") for (int k = 0; k < 2; ++k) dst[n][k] = *(const LAS bf16x8*)(lds + PG8_SB(b, h) + boffk[k] + n * 2048); } while (0)
; #define PG8_WAIT_V(n) asm volatile("s_waitcnt vmcnt(" #n ")" ::: "memory")
; #define PG8_WAIT_L(n) asm volatile("s_waitcnt lgkmcnt(" #n ")" ::: "memory")
; #define PG8_BAR __builtin_amdgcn_s_barrier()
; #define PG8_SCHED __builtin_amdgcn_sched_barrier(0)
; template <class Epi, class Sched, class GemmT>
; __device__ __forceinline__ void gemm_phase(LAS unsigned char* lds, const GemmT& g, const Sched& S, const Epi& E, const int wid) {
;     ...
;             for (int t = 0; t < nt; t += 2) {
;                 const bool last = (t == nt - 2);
;                 const char* a1 = cA + (size_t)(t + 1) * kstep;
;                 const char* a2 = last ? ns.A : cA + (size_t)(t + 2) * kstep; const char* b2 = last ? ns.B : cB + (size_t)(t + 2) * kstep;
;                 const char* a3 = a2 + kstep; const char* b3 = b2 + kstep;
;                 unsigned vA2[2], vB2[2];
; #pragma unroll
;                 for (int i = 0; i < 2; ++i) { vA2[i] = last ? nvA[i] : voffA[i]; vB2[i] = last ? nvB[i] : voffB[i]; }
;                 const size_t hA2 = last ? nhA : hstepA, hB2 = last ? nhB : hstepB;
;                 PG8_LDB(B0, 0, 0); PG8_LDB(B1, 0, 1); PG8_SCHED; PG8_LDA(At, 0, 0); PG8_STAGE(PG8_SA(1, 1), a1 + hstepA, voffA);
;                 PG8_WAIT_V(8); PG8_WAIT_L(0); PG8_BAR; PG8_MMA(0, 0, At, B0); PG8_MMA(0, 1, At, B1); PG8_BAR; PG8_SCHED;
;                 PG8_LDA(At, 0, 1); PG8_STAGE(PG8_SB(0, 0), b2, vB2); PG8_STAGE(PG8_SB(0, 1), b2 + hB2, vB2); PG8_STAGE(PG8_SA(0, 0), a2, vA2);
;                 PG8_WAIT_V(8); PG8_WAIT_L(0); PG8_BAR; PG8_MMA(1, 0, At, B0); PG8_MMA(1, 1, At, B1); PG8_BAR; PG8_SCHED;
.LBB0_1096:
	ds_read_b128 v[128:131], v188
	ds_read_b128 v[132:135], v189
	ds_read_b128 v[136:139], v190
	ds_read_b128 v[140:143], v191
	ds_read_b128 v[144:147], v192
	ds_read_b128 v[148:151], v193
	ds_read_b128 v[152:155], v194
	ds_read_b128 v[156:159], v195
	s_add_u32 s24, s22, 0xffd50080
	s_addc_u32 s25, s23, -1
	s_cmpk_eq_i32 s56, 0xa8
	s_cselect_b32 s27, s19, s25
	s_cselect_b32 s26, s18, s24
	s_cselect_b32 s25, s53, s55
	s_cselect_b32 s24, s52, s54
	v_lshl_add_u64 v[222:223], s[22:23], 0, v[168:169]
	s_add_i32 m0, s34, 0xc000
	ds_read_b128 v[160:163], v196
	ds_read_b128 v[164:167], v196 offset:2048
	ds_read_b128 v[180:183], v197
	ds_read_b128 v[202:205], v197 offset:2048
	ds_read_b128 v[206:209], v196 offset:4096
	ds_read_b128 v[210:213], v196 offset:6144
	ds_read_b128 v[214:217], v197 offset:4096
	ds_read_b128 v[218:221], v197 offset:6144
	global_load_lds_dwordx4 v[222:223], off
	v_lshl_add_u64 v[222:223], s[22:23], 0, v[172:173]
	s_add_i32 m0, s34, 0xe000
	s_nop 0
	global_load_lds_dwordx4 v[222:223], off
	s_waitcnt vmcnt(8)
	s_waitcnt lgkmcnt(0)
	s_barrier
	s_setprio 3
	s_waitcnt lgkmcnt(0)
	v_mfma_f32_16x16x32_bf16 v[124:127], v[128:131], v[160:163], v[124:127]
	v_mfma_f32_16x16x32_bf16 v[124:127], v[132:135], v[180:183], v[124:127]
	v_mfma_f32_16x16x32_bf16 v[120:123], v[140:143], v[180:183], v[120:123]
	v_mfma_f32_16x16x32_bf16 v[120:123], v[136:139], v[160:163], v[120:123]
	v_mfma_f32_16x16x32_bf16 v[104:107], v[136:139], v[164:167], v[104:107]
	v_mfma_f32_16x16x32_bf16 v[104:107], v[140:143], v[202:205], v[104:107]
	v_mfma_f32_16x16x32_bf16 v[112:115], v[132:135], v[202:205], v[112:115]
	v_mfma_f32_16x16x32_bf16 v[112:115], v[128:131], v[164:167], v[112:115]
	v_mfma_f32_16x16x32_bf16 v[96:99], v[128:131], v[206:209], v[96:99]
	v_mfma_f32_16x16x32_bf16 v[96:99], v[132:135], v[214:217], v[96:99]
	v_mfma_f32_16x16x32_bf16 v[88:91], v[140:143], v[214:217], v[88:91]
	v_mfma_f32_16x16x32_bf16 v[88:91], v[136:139], v[206:209], v[88:91]
	v_mfma_f32_16x16x32_bf16 v[72:75], v[136:139], v[210:213], v[72:75]
	v_mfma_f32_16x16x32_bf16 v[72:75], v[140:143], v[218:221], v[72:75]
	v_mfma_f32_16x16x32_bf16 v[80:83], v[132:135], v[218:221], v[80:83]
	v_mfma_f32_16x16x32_bf16 v[80:83], v[128:131], v[210:213], v[80:83]
	s_setprio 0
	s_setprio 3
	v_mfma_f32_16x16x32_bf16 v[116:119], v[144:147], v[160:163], v[116:119]
	v_mfma_f32_16x16x32_bf16 v[116:119], v[148:151], v[180:183], v[116:119]
	v_mfma_f32_16x16x32_bf16 v[108:111], v[156:159], v[180:183], v[108:111]
	v_mfma_f32_16x16x32_bf16 v[108:111], v[152:155], v[160:163], v[108:111]
	v_mfma_f32_16x16x32_bf16 v[92:95], v[152:155], v[164:167], v[92:95]
	v_mfma_f32_16x16x32_bf16 v[92:95], v[156:159], v[202:205], v[92:95]
	v_mfma_f32_16x16x32_bf16 v[100:103], v[148:151], v[202:205], v[100:103]
	v_mfma_f32_16x16x32_bf16 v[100:103], v[144:147], v[164:167], v[100:103]
	v_mfma_f32_16x16x32_bf16 v[84:87], v[144:147], v[206:209], v[84:87]
	v_mfma_f32_16x16x32_bf16 v[84:87], v[148:151], v[214:217], v[84:87]
	v_mfma_f32_16x16x32_bf16 v[76:79], v[156:159], v[214:217], v[76:79]
	v_mfma_f32_16x16x32_bf16 v[76:79], v[152:155], v[206:209], v[76:79]
	v_mfma_f32_16x16x32_bf16 v[60:63], v[152:155], v[210:213], v[60:63]
	v_mfma_f32_16x16x32_bf16 v[60:63], v[156:159], v[218:221], v[60:63]
	v_mfma_f32_16x16x32_bf16 v[68:71], v[148:151], v[218:221], v[68:71]
	v_mfma_f32_16x16x32_bf16 v[68:71], v[144:147], v[210:213], v[68:71]
	s_setprio 0
	s_barrier
	s_add_i32 s57, s41, s68
	v_lshl_add_u64 v[222:223], s[24:25], 0, v[170:171]
	s_mov_b32 m0, s57
	ds_read_b128 v[160:163], v196 offset:16384
	ds_read_b128 v[164:167], v196 offset:18432
	ds_read_b128 v[180:183], v197 offset:16384
	ds_read_b128 v[202:205], v197 offset:18432
	ds_read_b128 v[206:209], v196 offset:20480
	ds_read_b128 v[210:213], v196 offset:22528
	ds_read_b128 v[214:217], v197 offset:20480
	ds_read_b128 v[218:221], v197 offset:22528
	global_load_lds_dwordx4 v[222:223], off
	s_add_i32 m0, s57, 0x2000
	s_add_u32 s58, s24, 0x2b0000
	v_lshl_add_u64 v[224:225], s[24:25], 0, v[174:175]
	s_addc_u32 s59, s25, 0
	s_add_i32 s57, s42, s68
	global_load_lds_dwordx4 v[224:225], off
	v_lshl_add_u64 v[226:227], s[58:59], 0, v[170:171]
	s_mov_b32 m0, s57
	v_lshl_add_u64 v[228:229], s[26:27], 0, v[172:173]
	global_load_lds_dwordx4 v[226:227], off
	v_lshl_add_u64 v[226:227], s[58:59], 0, v[174:175]
	s_add_i32 m0, s57, 0x2000
	s_nop 0
	global_load_lds_dwordx4 v[226:227], off
	v_lshl_add_u64 v[226:227], s[26:27], 0, v[168:169]
	s_mov_b32 m0, s34
	s_nop 0
	global_load_lds_dwordx4 v[226:227], off
	s_mov_b32 m0, s35
	s_nop 0
	global_load_lds_dwordx4 v[228:229], off
	s_waitcnt vmcnt(8)
	s_waitcnt lgkmcnt(0)
	s_barrier
; #define PG8_STAGE(bufoff, gbase, voff) do { _Pragma("unroll") for (int _i = 0; _i < 2; ++_i) \
;         __builtin_amdgcn_global_load_lds((const unsigned*)((const char*)(gbase) + (voff)[_i]), (LAS unsigned*)(lds + (bufoff) + ldsw + _i * 8192), 16, 0, 0); } while (0)
; #define PG8_LDA(dst, b, h) do { _Pragma("unroll") for (int m = 0; m < 4; ++m) _Pragma("unroll") for (int k = 0; k < 2; ++k) dst[m][k] = *(const LAS bf16x8*)(lds + PG8_SA(b, h) + aoffk[k] + m * 2048); } while (0)
; #define PG8_LDB(dst, b, h) do { _Pragma("unroll") for (int n = 0; n < 2; ++n) _Pragma("unroll") for (int k = 0; k < 2; ++k) dst[n][k] = *(const LAS bf16x8*)(lds + PG8_SB(b, h) + boffk[k] + n * 2048); } while (0)
; #define PG8_WAIT_V(n) asm volatile("s_waitcnt vmcnt(" #n ")" ::: "memory")
; #define PG8_WAIT_L(n) asm volatile("s_waitcnt lgkmcnt(" #n ")" ::: "memory")
; #define PG8_BAR __builtin_amdgcn_s_barrier()
; #define PG8_SCHED __builtin_amdgcn_sched_barrier(0)
; template <class Epi, class Sched, class GemmT>
; __device__ __forceinline__ void gemm_phase(LAS unsigned char* lds, const GemmT& g, const Sched& S, const Epi& E, const int wid) {
;     ...
;                 PG8_WAIT_V(8); PG8_WAIT_L(0); PG8_BAR; PG8_MMA(1, 0, At, B0); PG8_MMA(1, 1, At, B1); PG8_BAR; PG8_SCHED;
;                 PG8_LDB(B0, 1, 0); PG8_LDB(B1, 1, 1); PG8_SCHED; PG8_LDA(At, 1, 0); PG8_STAGE(PG8_SA(0, 1), a2 + hA2, vA2);
;                 PG8_WAIT_V(8); PG8_WAIT_L(0); PG8_BAR; PG8_MMA(0, 0, At, B0); PG8_MMA(0, 1, At, B1); PG8_BAR; PG8_SCHED;
	s_setprio 3
	s_waitcnt lgkmcnt(0)
	v_mfma_f32_16x16x32_bf16 v[52:55], v[128:131], v[160:163], v[52:55]
	v_mfma_f32_16x16x32_bf16 v[52:55], v[132:135], v[180:183], v[52:55]
	v_mfma_f32_16x16x32_bf16 v[48:51], v[140:143], v[180:183], v[48:51]
	v_mfma_f32_16x16x32_bf16 v[48:51], v[136:139], v[160:163], v[48:51]
	v_mfma_f32_16x16x32_bf16 v[32:35], v[136:139], v[164:167], v[32:35]
	v_mfma_f32_16x16x32_bf16 v[32:35], v[140:143], v[202:205], v[32:35]
	v_mfma_f32_16x16x32_bf16 v[36:39], v[132:135], v[202:205], v[36:39]
	v_mfma_f32_16x16x32_bf16 v[36:39], v[128:131], v[164:167], v[36:39]
	v_mfma_f32_16x16x32_bf16 v[20:23], v[128:131], v[206:209], v[20:23]
	v_mfma_f32_16x16x32_bf16 v[20:23], v[132:135], v[214:217], v[20:23]
	v_mfma_f32_16x16x32_bf16 v[8:11], v[140:143], v[214:217], v[8:11]
	v_mfma_f32_16x16x32_bf16 v[8:11], v[136:139], v[206:209], v[8:11]
	v_mfma_f32_16x16x32_bf16 v[0:3], v[136:139], v[210:213], v[0:3]
	v_mfma_f32_16x16x32_bf16 v[0:3], v[140:143], v[218:221], v[0:3]
	v_mfma_f32_16x16x32_bf16 v[4:7], v[132:135], v[218:221], v[4:7]
	v_mfma_f32_16x16x32_bf16 v[4:7], v[128:131], v[210:213], v[4:7]
	s_setprio 0
	s_setprio 3
	v_mfma_f32_16x16x32_bf16 v[64:67], v[144:147], v[160:163], v[64:67]
	v_mfma_f32_16x16x32_bf16 v[64:67], v[148:151], v[180:183], v[64:67]
	v_mfma_f32_16x16x32_bf16 v[56:59], v[156:159], v[180:183], v[56:59]
	v_mfma_f32_16x16x32_bf16 v[56:59], v[152:155], v[160:163], v[56:59]
	v_mfma_f32_16x16x32_bf16 v[40:43], v[152:155], v[164:167], v[40:43]
	v_mfma_f32_16x16x32_bf16 v[40:43], v[156:159], v[202:205], v[40:43]
	v_mfma_f32_16x16x32_bf16 v[44:47], v[148:151], v[202:205], v[44:47]
	v_mfma_f32_16x16x32_bf16 v[44:47], v[144:147], v[164:167], v[44:47]
	v_mfma_f32_16x16x32_bf16 v[28:31], v[144:147], v[206:209], v[28:31]
	v_mfma_f32_16x16x32_bf16 v[28:31], v[148:151], v[214:217], v[28:31]
	v_mfma_f32_16x16x32_bf16 v[24:27], v[156:159], v[214:217], v[24:27]
	v_mfma_f32_16x16x32_bf16 v[24:27], v[152:155], v[206:209], v[24:27]
	v_mfma_f32_16x16x32_bf16 v[12:15], v[152:155], v[210:213], v[12:15]
	v_mfma_f32_16x16x32_bf16 v[12:15], v[156:159], v[218:221], v[12:15]
	v_mfma_f32_16x16x32_bf16 v[16:19], v[148:151], v[218:221], v[16:19]
	v_mfma_f32_16x16x32_bf16 v[16:19], v[144:147], v[210:213], v[16:19]
	s_setprio 0
	s_barrier
	s_add_i32 s57, 0, 0x18000
	s_add_i32 s58, 0, 0x1c000
	v_add_u32_e32 v128, s57, v185
	v_add_u32_e32 v132, s57, v186
	v_add_u32_e32 v144, s58, v185
	v_add_u32_e32 v148, s58, v186
	ds_read_b128 v[128:131], v128
	ds_read_b128 v[132:135], v132
	ds_read_b128 v[136:139], v198
	ds_read_b128 v[140:143], v199
	ds_read_b128 v[144:147], v144
	ds_read_b128 v[148:151], v148
	ds_read_b128 v[152:155], v200
	ds_read_b128 v[156:159], v201
	s_add_u32 s26, s26, 0x2b0000
	s_addc_u32 s27, s27, 0
	s_mov_b32 m0, s36
	v_lshl_add_u64 v[230:231], s[26:27], 0, v[168:169]
	ds_read_b128 v[160:163], v196 offset:32768
	ds_read_b128 v[164:167], v196 offset:34816
	ds_read_b128 v[180:183], v197 offset:32768
	ds_read_b128 v[202:205], v197 offset:34816
	ds_read_b128 v[206:209], v196 offset:36864
	ds_read_b128 v[210:213], v196 offset:38912
	ds_read_b128 v[214:217], v197 offset:36864
	ds_read_b128 v[218:221], v197 offset:38912
	global_load_lds_dwordx4 v[230:231], off
	v_lshl_add_u64 v[230:231], s[26:27], 0, v[172:173]
	s_mov_b32 m0, s37
	s_nop 0
	global_load_lds_dwordx4 v[230:231], off
	s_waitcnt vmcnt(8)
	s_waitcnt lgkmcnt(0)
	s_barrier
	s_setprio 3
	s_waitcnt lgkmcnt(0)
	v_mfma_f32_16x16x32_bf16 v[124:127], v[128:131], v[160:163], v[124:127]
	v_mfma_f32_16x16x32_bf16 v[124:127], v[132:135], v[180:183], v[124:127]
	v_mfma_f32_16x16x32_bf16 v[120:123], v[140:143], v[180:183], v[120:123]
	v_mfma_f32_16x16x32_bf16 v[120:123], v[136:139], v[160:163], v[120:123]
	v_mfma_f32_16x16x32_bf16 v[104:107], v[136:139], v[164:167], v[104:107]
	v_mfma_f32_16x16x32_bf16 v[104:107], v[140:143], v[202:205], v[104:107]
	v_mfma_f32_16x16x32_bf16 v[112:115], v[132:135], v[202:205], v[112:115]
	v_mfma_f32_16x16x32_bf16 v[112:115], v[128:131], v[164:167], v[112:115]
	v_mfma_f32_16x16x32_bf16 v[96:99], v[128:131], v[206:209], v[96:99]
	v_mfma_f32_16x16x32_bf16 v[96:99], v[132:135], v[214:217], v[96:99]
	v_mfma_f32_16x16x32_bf16 v[88:91], v[140:143], v[214:217], v[88:91]
	v_mfma_f32_16x16x32_bf16 v[88:91], v[136:139], v[206:209], v[88:91]
	v_mfma_f32_16x16x32_bf16 v[72:75], v[136:139], v[210:213], v[72:75]
	v_mfma_f32_16x16x32_bf16 v[72:75], v[140:143], v[218:221], v[72:75]
	v_mfma_f32_16x16x32_bf16 v[80:83], v[132:135], v[218:221], v[80:83]
	v_mfma_f32_16x16x32_bf16 v[80:83], v[128:131], v[210:213], v[80:83]
	s_setprio 0
	s_setprio 3
	v_mfma_f32_16x16x32_bf16 v[116:119], v[144:147], v[160:163], v[116:119]
	v_mfma_f32_16x16x32_bf16 v[116:119], v[148:151], v[180:183], v[116:119]
	v_mfma_f32_16x16x32_bf16 v[108:111], v[156:159], v[180:183], v[108:111]
	v_mfma_f32_16x16x32_bf16 v[108:111], v[152:155], v[160:163], v[108:111]
	v_mfma_f32_16x16x32_bf16 v[92:95], v[152:155], v[164:167], v[92:95]
	v_mfma_f32_16x16x32_bf16 v[92:95], v[156:159], v[202:205], v[92:95]
	v_mfma_f32_16x16x32_bf16 v[100:103], v[148:151], v[202:205], v[100:103]
	v_mfma_f32_16x16x32_bf16 v[100:103], v[144:147], v[164:167], v[100:103]
	v_mfma_f32_16x16x32_bf16 v[84:87], v[144:147], v[206:209], v[84:87]
	v_mfma_f32_16x16x32_bf16 v[84:87], v[148:151], v[214:217], v[84:87]
	v_mfma_f32_16x16x32_bf16 v[76:79], v[156:159], v[214:217], v[76:79]
	v_mfma_f32_16x16x32_bf16 v[76:79], v[152:155], v[206:209], v[76:79]
	v_mfma_f32_16x16x32_bf16 v[60:63], v[152:155], v[210:213], v[60:63]
	v_mfma_f32_16x16x32_bf16 v[60:63], v[156:159], v[218:221], v[60:63]
	v_mfma_f32_16x16x32_bf16 v[68:71], v[148:151], v[218:221], v[68:71]
	v_mfma_f32_16x16x32_bf16 v[68:71], v[144:147], v[210:213], v[68:71]
	s_setprio 0
	s_barrier
; #define PG8_STAGE(bufoff, gbase, voff) do { _Pragma("unroll") for (int _i = 0; _i < 2; ++_i) \
;         __builtin_amdgcn_global_load_lds((const unsigned*)((const char*)(gbase) + (voff)[_i]), (LAS unsigned*)(lds + (bufoff) + ldsw + _i * 8192), 16, 0, 0); } while (0)
; #define PG8_LDA(dst, b, h) do { _Pragma("unroll") for (int m = 0; m < 4; ++m) _Pragma("unroll") for (int k = 0; k < 2; ++k) dst[m][k] = *(const LAS bf16x8*)(lds + PG8_SA(b, h) + aoffk[k] + m * 2048); } while (0)
; #define PG8_WAIT_V(n) asm volatile("s_waitcnt vmcnt(" #n ")" ::: "memory")
; #define PG8_WAIT_L(n) asm volatile("s_waitcnt lgkmcnt(" #n ")" ::: "memory")
; #define PG8_BAR __builtin_amdgcn_s_barrier()
; #define PG8_SCHED __builtin_amdgcn_sched_barrier(0)
; template <class Epi, class Sched, class GemmT>
; __device__ __forceinline__ void gemm_phase(LAS unsigned char* lds, const GemmT& g, const Sched& S, const Epi& E, const int wid) {
;     ...
;                 PG8_LDA(At, 1, 1); PG8_STAGE(PG8_SB(1, 0), b3, vB2); PG8_STAGE(PG8_SB(1, 1), b3 + hB2, vB2); PG8_STAGE(PG8_SA(1, 0), a3, vA2);
;                 PG8_WAIT_V(8); PG8_WAIT_L(0); PG8_BAR; PG8_MMA(1, 0, At, B0); PG8_MMA(1, 1, At, B1); PG8_BAR; PG8_SCHED;
;             }
;             if constexpr (NSEG > 1) { if (sgi + 1 < NSEG) E.mid(acc, cur, sgi, wr, wc, fr, fq); }
;             cs = ns; cA = ns.A; cB = ns.B; hstepA = nhA; hstepB = nhB;
; #pragma unroll
;             for (int i = 0; i < 2; ++i) { voffA[i] = nvA[i]; voffB[i] = nvB[i]; }
;         }
;         if (wr == 0) PG8_BAR;
	s_add_i32 s26, s57, s68
	v_lshl_add_u64 v[222:223], v[222:223], 0, s[6:7]
	s_mov_b32 m0, s26
	ds_read_b128 v[160:163], v196 offset:49152
	ds_read_b128 v[164:167], v196 offset:51200
	ds_read_b128 v[180:183], v197 offset:49152
	ds_read_b128 v[202:205], v197 offset:51200
	ds_read_b128 v[206:209], v196 offset:53248
	ds_read_b128 v[210:213], v196 offset:55296
	ds_read_b128 v[214:217], v197 offset:53248
	ds_read_b128 v[218:221], v197 offset:55296
	global_load_lds_dwordx4 v[222:223], off
	s_add_i32 m0, s26, 0x2000
	s_add_u32 s24, s24, 0x2b0080
	v_lshl_add_u64 v[222:223], v[224:225], 0, s[6:7]
	s_addc_u32 s25, s25, 0
	s_add_i32 s26, s58, s68
	global_load_lds_dwordx4 v[222:223], off
	v_lshl_add_u64 v[222:223], s[24:25], 0, v[170:171]
	s_mov_b32 m0, s26
	s_nop 0
	global_load_lds_dwordx4 v[222:223], off
	v_lshl_add_u64 v[222:223], s[24:25], 0, v[174:175]
	s_add_i32 m0, s26, 0x2000
	s_nop 0
	global_load_lds_dwordx4 v[222:223], off
	v_lshl_add_u64 v[222:223], v[226:227], 0, s[6:7]
	s_mov_b32 m0, s39
	s_nop 0
	global_load_lds_dwordx4 v[222:223], off
	v_lshl_add_u64 v[222:223], v[228:229], 0, s[6:7]
	s_mov_b32 m0, s40
	s_nop 0
	global_load_lds_dwordx4 v[222:223], off
	s_waitcnt vmcnt(8)
	s_waitcnt lgkmcnt(0)
	s_barrier
	s_setprio 3
	s_waitcnt lgkmcnt(0)
	v_mfma_f32_16x16x32_bf16 v[52:55], v[128:131], v[160:163], v[52:55]
	v_mfma_f32_16x16x32_bf16 v[52:55], v[132:135], v[180:183], v[52:55]
	v_mfma_f32_16x16x32_bf16 v[48:51], v[140:143], v[180:183], v[48:51]
	v_mfma_f32_16x16x32_bf16 v[48:51], v[136:139], v[160:163], v[48:51]
	v_mfma_f32_16x16x32_bf16 v[32:35], v[136:139], v[164:167], v[32:35]
	v_mfma_f32_16x16x32_bf16 v[32:35], v[140:143], v[202:205], v[32:35]
	v_mfma_f32_16x16x32_bf16 v[36:39], v[132:135], v[202:205], v[36:39]
	v_mfma_f32_16x16x32_bf16 v[36:39], v[128:131], v[164:167], v[36:39]
	v_mfma_f32_16x16x32_bf16 v[20:23], v[128:131], v[206:209], v[20:23]
	v_mfma_f32_16x16x32_bf16 v[20:23], v[132:135], v[214:217], v[20:23]
	v_mfma_f32_16x16x32_bf16 v[8:11], v[140:143], v[214:217], v[8:11]
	v_mfma_f32_16x16x32_bf16 v[8:11], v[136:139], v[206:209], v[8:11]
	v_mfma_f32_16x16x32_bf16 v[0:3], v[136:139], v[210:213], v[0:3]
	v_mfma_f32_16x16x32_bf16 v[0:3], v[140:143], v[218:221], v[0:3]
	v_mfma_f32_16x16x32_bf16 v[4:7], v[132:135], v[218:221], v[4:7]
	v_mfma_f32_16x16x32_bf16 v[4:7], v[128:131], v[210:213], v[4:7]
	s_setprio 0
	s_setprio 3
	v_mfma_f32_16x16x32_bf16 v[64:67], v[144:147], v[160:163], v[64:67]
	v_mfma_f32_16x16x32_bf16 v[64:67], v[148:151], v[180:183], v[64:67]
	v_mfma_f32_16x16x32_bf16 v[56:59], v[156:159], v[180:183], v[56:59]
	v_mfma_f32_16x16x32_bf16 v[56:59], v[152:155], v[160:163], v[56:59]
	v_mfma_f32_16x16x32_bf16 v[40:43], v[152:155], v[164:167], v[40:43]
	v_mfma_f32_16x16x32_bf16 v[40:43], v[156:159], v[202:205], v[40:43]
	v_mfma_f32_16x16x32_bf16 v[44:47], v[148:151], v[202:205], v[44:47]
	v_mfma_f32_16x16x32_bf16 v[44:47], v[144:147], v[164:167], v[44:47]
	v_mfma_f32_16x16x32_bf16 v[28:31], v[144:147], v[206:209], v[28:31]
	v_mfma_f32_16x16x32_bf16 v[28:31], v[148:151], v[214:217], v[28:31]
	v_mfma_f32_16x16x32_bf16 v[24:27], v[156:159], v[214:217], v[24:27]
	v_mfma_f32_16x16x32_bf16 v[24:27], v[152:155], v[206:209], v[24:27]
	v_mfma_f32_16x16x32_bf16 v[12:15], v[152:155], v[210:213], v[12:15]
	v_mfma_f32_16x16x32_bf16 v[12:15], v[156:159], v[218:221], v[12:15]
	v_mfma_f32_16x16x32_bf16 v[16:19], v[148:151], v[218:221], v[16:19]
	v_mfma_f32_16x16x32_bf16 v[16:19], v[144:147], v[210:213], v[16:19]
	s_setprio 0
	s_barrier
	s_add_i32 s56, s56, 2
	s_add_u32 s22, s22, 0x100
	s_addc_u32 s23, s23, 0
	s_add_u32 s54, s54, 0x100
	s_addc_u32 s55, s55, 0
	s_cmpk_gt_u32 s56, 0xa9
	s_cbranch_scc0 .LBB0_1096
	s_and_b64 vcc, exec, s[8:9]
	s_cbranch_vccz .LBB0_1099
	s_barrier
